# K-loop: ds_reads of k=0 fragments issued first, counted lgkmcnt ladder recomputed
# baseline (speedup 1.0000x reference)
; #define PG8_STAGE(bufoff, gbase, voff) do { _Pragma("unroll") for (int _i = 0; _i < 2; ++_i) \
;         __builtin_amdgcn_global_load_lds((const unsigned*)((const char*)(gbase) + (voff)[_i]), (LAS unsigned*)(lds + (bufoff) + ldsw + _i * 8192), 16, 0, 0); } while (0)
; #define PG8_LDA(dst, b, h) do { _Pragma("unroll") for (int m = 0; m < 4; ++m) _Pragma("unroll") for (int k = 0; k < 2; ++k) dst[m][k] = *(const LAS bf16x8*)(lds + PG8_SA(b, h) + aoff + m * 2048 + k * 1024); } while (0)
; #define PG8_LDB(dst, b, h) do { _Pragma("unroll") for (int n = 0; n < 2; ++n) _Pragma("unroll") for (int k = 0; k < 2; ++k) dst[n][k] = *(const LAS bf16x8*)(lds + PG8_SB(b, h) + boff + n * 2048 + k * 1024); } while (0)
; #define PG8_MMA(ai, bj, At, Bt) do { __builtin_amdgcn_s_setprio(1); _Pragma("unroll") for (int m = 0; m < 4; ++m) _Pragma("unroll") for (int n = 0; n < 2; ++n) _Pragma("unroll") for (int k = 0; k < 2; ++k) \
;         acc[ai][bj][m][n] = __builtin_amdgcn_mfma_f32_16x16x32_bf16(Bt[n][k], At[m][k], acc[ai][bj][m][n], 0, 0, 0); __builtin_amdgcn_s_setprio(0); } while (0)
; #define PG8_WAIT_L(n) asm volatile("s_waitcnt lgkmcnt(" #n ")" ::: "memory")
; template <class Epi>
; __device__ __forceinline__ void gemm_phase(LAS unsigned char* lds, const Gemm g, const StaticOrder& S, const Epi& E) {
;     ...
;         const bool has_next = S.next(ui + 1, nxt);
;         const char* nA = has_next ? (const char*)g.A + (size_t)nxt.pm * tstepA : cA; const char* nB = has_next ? (const char*)g.Bt + (size_t)nxt.pn * tstepB : cB;
;         for (int t = 0; t < nt; t += 2) {
;             const bool last = (t == nt - 2);
;             const char* a1 = cA + (size_t)(t + 1) * kstep;
;             const char* a2 = last ? nA : cA + (size_t)(t + 2) * kstep; const char* b2 = last ? nB : cB + (size_t)(t + 2) * kstep;
;             const char* a3 = a2 + kstep; const char* b3 = b2 + kstep;
;             PG8_LDB(B0, 0, 0); PG8_SCHED; PG8_LDA(At, 0, 0); PG8_STAGE(PG8_SA(1, 1), a1 + hstepA, voffA);
;             PG8_WAIT_L(8); PG8_BAR; PG8_WAIT_L(0); PG8_MMA(0, 0, At, B0); PG8_BAR; PG8_SCHED;
;             PG8_LDB(B1, 0, 1); PG8_STAGE(PG8_SB(0, 0), b2, voffB);
;             PG8_BAR; PG8_WAIT_L(0); PG8_MMA(0, 1, At, B1); PG8_BAR;
;             PG8_LDA(At, 0, 1); PG8_STAGE(PG8_SA(0, 0), a2, voffA);
;             PG8_BAR; PG8_WAIT_L(0); PG8_MMA(1, 0, At, B0); PG8_BAR; PG8_SCHED;
.LBB0_140:
	v_mov_b64_e32 v[0:1], 0x800
	s_ashr_i32 s15, s14, 31
	v_cmp_lt_i64_e32 vcc, s[16:17], v[0:1]
	s_lshl_b64 s[16:17], s[14:15], 20
	v_readlane_b32 s18, v252, 53
	v_readlane_b32 s19, v252, 54
	s_add_u32 s16, s18, s16
	s_addc_u32 s17, s19, s17
	s_and_b64 s[18:19], vcc, exec
	s_cselect_b32 s15, s17, s23
	s_cselect_b32 s49, s16, s22
	s_ashr_i32 s5, s4, 31
	s_lshl_b64 s[18:19], s[4:5], 20
	s_add_u32 s18, s34, s18
	s_addc_u32 s19, s35, s19
	s_and_b64 s[26:27], vcc, exec
	s_cselect_b32 s5, s19, s25
	s_cselect_b32 s50, s18, s24
	s_add_u32 s22, s22, 0x84000
	s_addc_u32 s23, s23, 0
	s_add_u32 s51, s24, 0x8000
	s_addc_u32 s52, s25, 0
	s_mov_b32 s54, -2
	s_add_u32 s24, s22, 0xfff84000
	s_addc_u32 s25, s23, -1
	s_cmp_eq_u32 s54, 28
	s_cselect_b32 s28, s49, s24
	s_cselect_b32 s29, s15, s25
	s_cselect_b32 s24, s50, s51
	s_cselect_b32 s25, s5, s52
	s_add_u32 s26, s28, 0x4000
	s_addc_u32 s27, s29, 0
	s_add_i32 s55, 0, 0x10000
	v_add_u32_e32 v148, s55, v134
	ds_read_b128 v[136:139], v148
	ds_read_b128 v[144:147], v148 offset:2048
	ds_read_b128 v[140:143], v148 offset:1024
	ds_read_b128 v[148:151], v148 offset:3072
	v_lshl_add_u64 v[188:189], s[22:23], 0, v[128:129]
	s_add_i32 m0, s37, 0xc000
	ds_read_b128 v[156:159], v135
	ds_read_b128 v[164:167], v135 offset:2048
	ds_read_b128 v[172:175], v135 offset:4096
	ds_read_b128 v[180:183], v135 offset:6144
	ds_read_b128 v[160:163], v135 offset:1024
	ds_read_b128 v[168:171], v135 offset:3072
	ds_read_b128 v[176:179], v135 offset:5120
	ds_read_b128 v[184:187], v135 offset:7168
	global_load_lds_dwordx4 v[188:189], off
	s_add_i32 m0, s37, 0xe000
	v_lshl_add_u64 v[188:189], s[22:23], 0, v[130:131]
	global_load_lds_dwordx4 v[188:189], off
	s_waitcnt lgkmcnt(8)
	s_barrier
	s_waitcnt lgkmcnt(7)
	v_mfma_f32_16x16x32_bf16 v[124:127], v[136:139], v[156:159], 0
	s_setprio 1
	v_mfma_f32_16x16x32_bf16 v[120:123], v[144:147], v[156:159], 0
	s_waitcnt lgkmcnt(6)
	v_mfma_f32_16x16x32_bf16 v[108:111], v[136:139], v[164:167], 0
	v_mfma_f32_16x16x32_bf16 v[104:107], v[144:147], v[164:167], 0
	s_waitcnt lgkmcnt(5)
	v_mfma_f32_16x16x32_bf16 v[92:95], v[136:139], v[172:175], 0
	v_mfma_f32_16x16x32_bf16 v[88:91], v[144:147], v[172:175], 0
	s_waitcnt lgkmcnt(4)
	v_mfma_f32_16x16x32_bf16 v[76:79], v[136:139], v[180:183], 0
	v_mfma_f32_16x16x32_bf16 v[72:75], v[144:147], v[180:183], 0
	s_waitcnt lgkmcnt(3)
	v_mfma_f32_16x16x32_bf16 v[124:127], v[140:143], v[160:163], v[124:127]
	v_mfma_f32_16x16x32_bf16 v[120:123], v[148:151], v[160:163], v[120:123]
	s_waitcnt lgkmcnt(2)
	v_mfma_f32_16x16x32_bf16 v[108:111], v[140:143], v[168:171], v[108:111]
	v_mfma_f32_16x16x32_bf16 v[104:107], v[148:151], v[168:171], v[104:107]
	s_waitcnt lgkmcnt(1)
	v_mfma_f32_16x16x32_bf16 v[92:95], v[140:143], v[176:179], v[92:95]
	v_mfma_f32_16x16x32_bf16 v[88:91], v[148:151], v[176:179], v[88:91]
	s_waitcnt lgkmcnt(0)
	v_mfma_f32_16x16x32_bf16 v[76:79], v[140:143], v[184:187], v[76:79]
	s_setprio 0
	v_mfma_f32_16x16x32_bf16 v[72:75], v[148:151], v[184:187], v[72:75]
	s_barrier
	s_add_i32 s58, 0, 0x14000
	s_add_i32 s55, s55, s36
	v_add_u32_e32 v152, s58, v134
	v_lshl_add_u64 v[204:205], s[24:25], 0, v[128:129]
	s_mov_b32 m0, s55
	ds_read_b128 v[188:191], v152
	ds_read_b128 v[196:199], v152 offset:2048
	ds_read_b128 v[192:195], v152 offset:1024
	ds_read_b128 v[200:203], v152 offset:3072
	global_load_lds_dwordx4 v[204:205], off
	s_add_i32 m0, s55, 0x2000
	v_lshl_add_u64 v[204:205], s[24:25], 0, v[130:131]
	global_load_lds_dwordx4 v[204:205], off
	s_barrier
	s_waitcnt lgkmcnt(3)
	v_mfma_f32_16x16x32_bf16 v[116:119], v[188:191], v[156:159], 0
	s_setprio 1
	s_waitcnt lgkmcnt(2)
	v_mfma_f32_16x16x32_bf16 v[112:115], v[196:199], v[156:159], 0
	s_mov_b32 m0, s37
	v_lshl_add_u64 v[204:205], s[28:29], 0, v[128:129]
	v_mfma_f32_16x16x32_bf16 v[100:103], v[188:191], v[164:167], 0
	v_mfma_f32_16x16x32_bf16 v[96:99], v[196:199], v[164:167], 0
	v_mfma_f32_16x16x32_bf16 v[84:87], v[188:191], v[172:175], 0
	v_mfma_f32_16x16x32_bf16 v[80:83], v[196:199], v[172:175], 0
	v_mfma_f32_16x16x32_bf16 v[68:71], v[188:191], v[180:183], 0
	v_mfma_f32_16x16x32_bf16 v[64:67], v[196:199], v[180:183], 0
	s_waitcnt lgkmcnt(1)
	v_mfma_f32_16x16x32_bf16 v[116:119], v[192:195], v[160:163], v[116:119]
	s_waitcnt lgkmcnt(0)
	v_mfma_f32_16x16x32_bf16 v[112:115], v[200:203], v[160:163], v[112:115]
	v_mfma_f32_16x16x32_bf16 v[100:103], v[192:195], v[168:171], v[100:103]
	v_mfma_f32_16x16x32_bf16 v[96:99], v[200:203], v[168:171], v[96:99]
	v_mfma_f32_16x16x32_bf16 v[84:87], v[192:195], v[176:179], v[84:87]
	v_mfma_f32_16x16x32_bf16 v[80:83], v[200:203], v[176:179], v[80:83]
	v_mfma_f32_16x16x32_bf16 v[68:71], v[192:195], v[184:187], v[68:71]
	s_setprio 0
	v_mfma_f32_16x16x32_bf16 v[64:67], v[200:203], v[184:187], v[64:67]
	s_barrier
	ds_read_b128 v[156:159], v135 offset:16384
	ds_read_b128 v[164:167], v135 offset:18432
	ds_read_b128 v[172:175], v135 offset:20480
	ds_read_b128 v[180:183], v135 offset:22528
	ds_read_b128 v[160:163], v135 offset:17408
	ds_read_b128 v[168:171], v135 offset:19456
	ds_read_b128 v[176:179], v135 offset:21504
	ds_read_b128 v[184:187], v135 offset:23552
	global_load_lds_dwordx4 v[204:205], off
	s_mov_b32 m0, s38
	v_lshl_add_u64 v[204:205], s[28:29], 0, v[130:131]
	global_load_lds_dwordx4 v[204:205], off
	s_barrier
; #define PG8_STAGE(bufoff, gbase, voff) do { _Pragma("unroll") for (int _i = 0; _i < 2; ++_i) \
;         __builtin_amdgcn_global_load_lds((const unsigned*)((const char*)(gbase) + (voff)[_i]), (LAS unsigned*)(lds + (bufoff) + ldsw + _i * 8192), 16, 0, 0); } while (0)
; #define PG8_LDA(dst, b, h) do { _Pragma("unroll") for (int m = 0; m < 4; ++m) _Pragma("unroll") for (int k = 0; k < 2; ++k) dst[m][k] = *(const LAS bf16x8*)(lds + PG8_SA(b, h) + aoff + m * 2048 + k * 1024); } while (0)
; #define PG8_LDB(dst, b, h) do { _Pragma("unroll") for (int n = 0; n < 2; ++n) _Pragma("unroll") for (int k = 0; k < 2; ++k) dst[n][k] = *(const LAS bf16x8*)(lds + PG8_SB(b, h) + boff + n * 2048 + k * 1024); } while (0)
; #define PG8_MMA(ai, bj, At, Bt) do { __builtin_amdgcn_s_setprio(1); _Pragma("unroll") for (int m = 0; m < 4; ++m) _Pragma("unroll") for (int n = 0; n < 2; ++n) _Pragma("unroll") for (int k = 0; k < 2; ++k) \
;         acc[ai][bj][m][n] = __builtin_amdgcn_mfma_f32_16x16x32_bf16(Bt[n][k], At[m][k], acc[ai][bj][m][n], 0, 0, 0); __builtin_amdgcn_s_setprio(0); } while (0)
; #define PG8_WAIT_V(n) asm volatile("s_waitcnt vmcnt(" #n ")" ::: "memory")
; #define PG8_WAIT_L(n) asm volatile("s_waitcnt lgkmcnt(" #n ")" ::: "memory")
; #define PG8_BAR __builtin_amdgcn_s_barrier()
; #define PG8_SCHED __builtin_amdgcn_sched_barrier(0)
; template <class Epi>
; __device__ __forceinline__ void gemm_phase(LAS unsigned char* lds, const Gemm g, const StaticOrder& S, const Epi& E) {
;     ...
;             PG8_BAR; PG8_WAIT_L(0); PG8_MMA(1, 0, At, B0); PG8_BAR; PG8_SCHED;
;             PG8_STAGE(PG8_SB(0, 1), b2 + hstepB, voffB);
;             PG8_WAIT_V(6); PG8_BAR; PG8_MMA(1, 1, At, B1); PG8_BAR;
;             PG8_LDB(B0, 1, 0); PG8_SCHED; PG8_LDA(At, 1, 0); PG8_STAGE(PG8_SA(0, 1), a2 + hstepA, voffA);
;             PG8_WAIT_L(8); PG8_BAR; PG8_WAIT_L(0); PG8_MMA(0, 0, At, B0); PG8_BAR; PG8_SCHED;
;             PG8_LDB(B1, 1, 1); PG8_STAGE(PG8_SB(1, 0), b3, voffB);
;             PG8_BAR; PG8_WAIT_L(0); PG8_MMA(0, 1, At, B1); PG8_BAR;
	s_waitcnt lgkmcnt(7)
	v_mfma_f32_16x16x32_bf16 v[60:63], v[136:139], v[156:159], 0
	s_setprio 1
	v_mfma_f32_16x16x32_bf16 v[56:59], v[144:147], v[156:159], 0
	s_waitcnt lgkmcnt(6)
	v_mfma_f32_16x16x32_bf16 v[44:47], v[136:139], v[164:167], 0
	v_mfma_f32_16x16x32_bf16 v[40:43], v[144:147], v[164:167], 0
	s_waitcnt lgkmcnt(5)
	v_mfma_f32_16x16x32_bf16 v[28:31], v[136:139], v[172:175], 0
	v_mfma_f32_16x16x32_bf16 v[24:27], v[144:147], v[172:175], 0
	s_waitcnt lgkmcnt(4)
	v_mfma_f32_16x16x32_bf16 v[12:15], v[136:139], v[180:183], 0
	v_mfma_f32_16x16x32_bf16 v[8:11], v[144:147], v[180:183], 0
	s_waitcnt lgkmcnt(3)
	v_mfma_f32_16x16x32_bf16 v[60:63], v[140:143], v[160:163], v[60:63]
	v_mfma_f32_16x16x32_bf16 v[56:59], v[148:151], v[160:163], v[56:59]
	s_waitcnt lgkmcnt(2)
	v_mfma_f32_16x16x32_bf16 v[44:47], v[140:143], v[168:171], v[44:47]
	v_mfma_f32_16x16x32_bf16 v[40:43], v[148:151], v[168:171], v[40:43]
	s_waitcnt lgkmcnt(1)
	v_mfma_f32_16x16x32_bf16 v[28:31], v[140:143], v[176:179], v[28:31]
	v_mfma_f32_16x16x32_bf16 v[24:27], v[148:151], v[176:179], v[24:27]
	s_waitcnt lgkmcnt(0)
	v_mfma_f32_16x16x32_bf16 v[12:15], v[140:143], v[184:187], v[12:15]
	s_setprio 0
	v_mfma_f32_16x16x32_bf16 v[8:11], v[148:151], v[184:187], v[8:11]
	s_barrier
	s_add_u32 s56, s24, 0x80000
	s_addc_u32 s57, s25, 0
	s_add_i32 s55, s58, s36
	s_mov_b32 m0, s55
	v_lshl_add_u64 v[136:137], s[56:57], 0, v[128:129]
	global_load_lds_dwordx4 v[136:137], off
	s_add_i32 m0, s55, 0x2000
	v_lshl_add_u64 v[136:137], s[56:57], 0, v[130:131]
	global_load_lds_dwordx4 v[136:137], off
	s_waitcnt vmcnt(6)
	s_barrier
	v_mfma_f32_16x16x32_bf16 v[52:55], v[188:191], v[156:159], 0
	s_setprio 1
	v_mfma_f32_16x16x32_bf16 v[48:51], v[196:199], v[156:159], 0
	s_add_i32 s55, 0, 0x18000
	v_add_u32_e32 v148, s55, v134
	v_mfma_f32_16x16x32_bf16 v[36:39], v[188:191], v[164:167], 0
	v_mfma_f32_16x16x32_bf16 v[32:35], v[196:199], v[164:167], 0
	v_mfma_f32_16x16x32_bf16 v[20:23], v[188:191], v[172:175], 0
	v_mfma_f32_16x16x32_bf16 v[16:19], v[196:199], v[172:175], 0
	v_mfma_f32_16x16x32_bf16 v[4:7], v[188:191], v[180:183], 0
	v_mfma_f32_16x16x32_bf16 v[0:3], v[196:199], v[180:183], 0
	v_mfma_f32_16x16x32_bf16 v[52:55], v[192:195], v[160:163], v[52:55]
	v_mfma_f32_16x16x32_bf16 v[48:51], v[200:203], v[160:163], v[48:51]
	v_mfma_f32_16x16x32_bf16 v[36:39], v[192:195], v[168:171], v[36:39]
	v_mfma_f32_16x16x32_bf16 v[32:35], v[200:203], v[168:171], v[32:35]
	v_mfma_f32_16x16x32_bf16 v[20:23], v[192:195], v[176:179], v[20:23]
	v_mfma_f32_16x16x32_bf16 v[16:19], v[200:203], v[176:179], v[16:19]
	v_mfma_f32_16x16x32_bf16 v[4:7], v[192:195], v[184:187], v[4:7]
	s_setprio 0
	v_mfma_f32_16x16x32_bf16 v[0:3], v[200:203], v[184:187], v[0:3]
	s_barrier
	ds_read_b128 v[136:139], v148
	ds_read_b128 v[144:147], v148 offset:2048
	ds_read_b128 v[140:143], v148 offset:1024
	ds_read_b128 v[148:151], v148 offset:3072
	s_add_u32 s28, s28, 0x80000
	s_addc_u32 s29, s29, 0
	s_mov_b32 m0, s39
	v_lshl_add_u64 v[188:189], s[28:29], 0, v[128:129]
	ds_read_b128 v[156:159], v135 offset:32768
	ds_read_b128 v[164:167], v135 offset:34816
	ds_read_b128 v[172:175], v135 offset:36864
	ds_read_b128 v[180:183], v135 offset:38912
	ds_read_b128 v[160:163], v135 offset:33792
	ds_read_b128 v[168:171], v135 offset:35840
	ds_read_b128 v[176:179], v135 offset:37888
	ds_read_b128 v[184:187], v135 offset:39936
	global_load_lds_dwordx4 v[188:189], off
	s_mov_b32 m0, s40
	v_lshl_add_u64 v[188:189], s[28:29], 0, v[130:131]
	global_load_lds_dwordx4 v[188:189], off
	s_waitcnt lgkmcnt(8)
	s_barrier
	s_waitcnt lgkmcnt(7)
	v_mfma_f32_16x16x32_bf16 v[124:127], v[136:139], v[156:159], v[124:127]
	s_setprio 1
	v_mfma_f32_16x16x32_bf16 v[120:123], v[144:147], v[156:159], v[120:123]
	s_waitcnt lgkmcnt(6)
	v_mfma_f32_16x16x32_bf16 v[108:111], v[136:139], v[164:167], v[108:111]
	v_mfma_f32_16x16x32_bf16 v[104:107], v[144:147], v[164:167], v[104:107]
	s_waitcnt lgkmcnt(5)
	v_mfma_f32_16x16x32_bf16 v[92:95], v[136:139], v[172:175], v[92:95]
	v_mfma_f32_16x16x32_bf16 v[88:91], v[144:147], v[172:175], v[88:91]
	s_waitcnt lgkmcnt(4)
	v_mfma_f32_16x16x32_bf16 v[76:79], v[136:139], v[180:183], v[76:79]
	v_mfma_f32_16x16x32_bf16 v[72:75], v[144:147], v[180:183], v[72:75]
	s_waitcnt lgkmcnt(3)
	v_mfma_f32_16x16x32_bf16 v[124:127], v[140:143], v[160:163], v[124:127]
	v_mfma_f32_16x16x32_bf16 v[120:123], v[148:151], v[160:163], v[120:123]
	s_waitcnt lgkmcnt(2)
	v_mfma_f32_16x16x32_bf16 v[108:111], v[140:143], v[168:171], v[108:111]
	v_mfma_f32_16x16x32_bf16 v[104:107], v[148:151], v[168:171], v[104:107]
	s_waitcnt lgkmcnt(1)
	v_mfma_f32_16x16x32_bf16 v[92:95], v[140:143], v[176:179], v[92:95]
	v_mfma_f32_16x16x32_bf16 v[88:91], v[148:151], v[176:179], v[88:91]
	s_waitcnt lgkmcnt(0)
	v_mfma_f32_16x16x32_bf16 v[76:79], v[140:143], v[184:187], v[76:79]
	s_setprio 0
	v_mfma_f32_16x16x32_bf16 v[72:75], v[148:151], v[184:187], v[72:75]
	s_barrier
	s_add_i32 s56, 0, 0x1c000
	s_add_u32 s28, s24, 0x4000
	s_addc_u32 s29, s25, 0
	s_add_i32 s55, s55, s36
	v_add_u32_e32 v152, s56, v134
	v_lshl_add_u64 v[204:205], s[28:29], 0, v[128:129]
	s_mov_b32 m0, s55
	ds_read_b128 v[188:191], v152
	ds_read_b128 v[196:199], v152 offset:2048
	ds_read_b128 v[192:195], v152 offset:1024
	ds_read_b128 v[200:203], v152 offset:3072
	global_load_lds_dwordx4 v[204:205], off
	s_add_i32 m0, s55, 0x2000
	v_lshl_add_u64 v[204:205], s[28:29], 0, v[130:131]
	global_load_lds_dwordx4 v[204:205], off
	s_barrier
; #define PG8_STAGE(bufoff, gbase, voff) do { _Pragma("unroll") for (int _i = 0; _i < 2; ++_i) \
;         __builtin_amdgcn_global_load_lds((const unsigned*)((const char*)(gbase) + (voff)[_i]), (LAS unsigned*)(lds + (bufoff) + ldsw + _i * 8192), 16, 0, 0); } while (0)
; #define PG8_LDA(dst, b, h) do { _Pragma("unroll") for (int m = 0; m < 4; ++m) _Pragma("unroll") for (int k = 0; k < 2; ++k) dst[m][k] = *(const LAS bf16x8*)(lds + PG8_SA(b, h) + aoff + m * 2048 + k * 1024); } while (0)
; #define PG8_MMA(ai, bj, At, Bt) do { __builtin_amdgcn_s_setprio(1); _Pragma("unroll") for (int m = 0; m < 4; ++m) _Pragma("unroll") for (int n = 0; n < 2; ++n) _Pragma("unroll") for (int k = 0; k < 2; ++k) \
;         acc[ai][bj][m][n] = __builtin_amdgcn_mfma_f32_16x16x32_bf16(Bt[n][k], At[m][k], acc[ai][bj][m][n], 0, 0, 0); __builtin_amdgcn_s_setprio(0); } while (0)
; #define PG8_WAIT_V(n) asm volatile("s_waitcnt vmcnt(" #n ")" ::: "memory")
; #define PG8_WAIT_L(n) asm volatile("s_waitcnt lgkmcnt(" #n ")" ::: "memory")
; #define PG8_BAR __builtin_amdgcn_s_barrier()
; #define PG8_SCHED __builtin_amdgcn_sched_barrier(0)
; template <class Epi>
; __device__ __forceinline__ void gemm_phase(LAS unsigned char* lds, const Gemm g, const StaticOrder& S, const Epi& E) {
;     ...
;             PG8_BAR; PG8_WAIT_L(0); PG8_MMA(0, 1, At, B1); PG8_BAR;
;             PG8_LDA(At, 1, 1); PG8_STAGE(PG8_SA(1, 0), a3, voffA);
;             PG8_BAR; PG8_WAIT_L(0); PG8_MMA(1, 0, At, B0); PG8_BAR; PG8_SCHED;
;             PG8_STAGE(PG8_SB(1, 1), b3 + hstepB, voffB);
;             PG8_WAIT_V(6); PG8_BAR; PG8_MMA(1, 1, At, B1); PG8_BAR;
;         }
	s_waitcnt lgkmcnt(3)
	v_mfma_f32_16x16x32_bf16 v[116:119], v[188:191], v[156:159], v[116:119]
	s_setprio 1
	s_waitcnt lgkmcnt(2)
	v_mfma_f32_16x16x32_bf16 v[112:115], v[196:199], v[156:159], v[112:115]
	s_mov_b32 m0, s43
	v_lshl_add_u64 v[204:205], s[26:27], 0, v[128:129]
	v_mfma_f32_16x16x32_bf16 v[100:103], v[188:191], v[164:167], v[100:103]
	v_mfma_f32_16x16x32_bf16 v[96:99], v[196:199], v[164:167], v[96:99]
	v_mfma_f32_16x16x32_bf16 v[84:87], v[188:191], v[172:175], v[84:87]
	v_mfma_f32_16x16x32_bf16 v[80:83], v[196:199], v[172:175], v[80:83]
	v_mfma_f32_16x16x32_bf16 v[68:71], v[188:191], v[180:183], v[68:71]
	v_mfma_f32_16x16x32_bf16 v[64:67], v[196:199], v[180:183], v[64:67]
	s_waitcnt lgkmcnt(1)
	v_mfma_f32_16x16x32_bf16 v[116:119], v[192:195], v[160:163], v[116:119]
	s_waitcnt lgkmcnt(0)
	v_mfma_f32_16x16x32_bf16 v[112:115], v[200:203], v[160:163], v[112:115]
	v_mfma_f32_16x16x32_bf16 v[100:103], v[192:195], v[168:171], v[100:103]
	v_mfma_f32_16x16x32_bf16 v[96:99], v[200:203], v[168:171], v[96:99]
	v_mfma_f32_16x16x32_bf16 v[84:87], v[192:195], v[176:179], v[84:87]
	v_mfma_f32_16x16x32_bf16 v[80:83], v[200:203], v[176:179], v[80:83]
	v_mfma_f32_16x16x32_bf16 v[68:71], v[192:195], v[184:187], v[68:71]
	s_setprio 0
	v_mfma_f32_16x16x32_bf16 v[64:67], v[200:203], v[184:187], v[64:67]
	s_barrier
	ds_read_b128 v[156:159], v135 offset:49152
	ds_read_b128 v[164:167], v135 offset:51200
	ds_read_b128 v[172:175], v135 offset:53248
	ds_read_b128 v[180:183], v135 offset:55296
	ds_read_b128 v[160:163], v135 offset:50176
	ds_read_b128 v[168:171], v135 offset:52224
	ds_read_b128 v[176:179], v135 offset:54272
	ds_read_b128 v[184:187], v135 offset:56320
	global_load_lds_dwordx4 v[204:205], off
	s_mov_b32 m0, s44
	v_lshl_add_u64 v[204:205], s[26:27], 0, v[130:131]
	global_load_lds_dwordx4 v[204:205], off
	s_barrier
	s_waitcnt lgkmcnt(7)
	v_mfma_f32_16x16x32_bf16 v[60:63], v[136:139], v[156:159], v[60:63]
	s_setprio 1
	v_mfma_f32_16x16x32_bf16 v[56:59], v[144:147], v[156:159], v[56:59]
	s_waitcnt lgkmcnt(6)
	v_mfma_f32_16x16x32_bf16 v[44:47], v[136:139], v[164:167], v[44:47]
	v_mfma_f32_16x16x32_bf16 v[40:43], v[144:147], v[164:167], v[40:43]
	s_waitcnt lgkmcnt(5)
	v_mfma_f32_16x16x32_bf16 v[28:31], v[136:139], v[172:175], v[28:31]
	v_mfma_f32_16x16x32_bf16 v[24:27], v[144:147], v[172:175], v[24:27]
	s_waitcnt lgkmcnt(4)
	v_mfma_f32_16x16x32_bf16 v[12:15], v[136:139], v[180:183], v[12:15]
	v_mfma_f32_16x16x32_bf16 v[8:11], v[144:147], v[180:183], v[8:11]
	s_waitcnt lgkmcnt(3)
	v_mfma_f32_16x16x32_bf16 v[60:63], v[140:143], v[160:163], v[60:63]
	v_mfma_f32_16x16x32_bf16 v[56:59], v[148:151], v[160:163], v[56:59]
	s_waitcnt lgkmcnt(2)
	v_mfma_f32_16x16x32_bf16 v[44:47], v[140:143], v[168:171], v[44:47]
	v_mfma_f32_16x16x32_bf16 v[40:43], v[148:151], v[168:171], v[40:43]
	s_waitcnt lgkmcnt(1)
	v_mfma_f32_16x16x32_bf16 v[28:31], v[140:143], v[176:179], v[28:31]
	v_mfma_f32_16x16x32_bf16 v[24:27], v[148:151], v[176:179], v[24:27]
	s_waitcnt lgkmcnt(0)
	v_mfma_f32_16x16x32_bf16 v[12:15], v[140:143], v[184:187], v[12:15]
	s_setprio 0
	v_mfma_f32_16x16x32_bf16 v[8:11], v[148:151], v[184:187], v[8:11]
	s_barrier
	s_add_u32 s24, s24, 0x84000
	s_addc_u32 s25, s25, 0
	s_add_i32 s26, s56, s36
	s_mov_b32 m0, s26
	v_lshl_add_u64 v[136:137], s[24:25], 0, v[128:129]
	global_load_lds_dwordx4 v[136:137], off
	s_add_i32 m0, s26, 0x2000
	v_lshl_add_u64 v[136:137], s[24:25], 0, v[130:131]
	global_load_lds_dwordx4 v[136:137], off
	s_waitcnt vmcnt(6)
	s_barrier
	v_mfma_f32_16x16x32_bf16 v[52:55], v[188:191], v[156:159], v[52:55]
	s_setprio 1
	v_mfma_f32_16x16x32_bf16 v[48:51], v[196:199], v[156:159], v[48:51]
	s_add_i32 s54, s54, 2
	s_add_u32 s22, s22, 0x8000
	s_addc_u32 s23, s23, 0
	s_add_u32 s51, s51, 0x8000
	s_addc_u32 s52, s52, 0
	v_mfma_f32_16x16x32_bf16 v[36:39], v[188:191], v[164:167], v[36:39]
	v_mfma_f32_16x16x32_bf16 v[32:35], v[196:199], v[164:167], v[32:35]
	v_mfma_f32_16x16x32_bf16 v[20:23], v[188:191], v[172:175], v[20:23]
	v_mfma_f32_16x16x32_bf16 v[16:19], v[196:199], v[172:175], v[16:19]
	v_mfma_f32_16x16x32_bf16 v[4:7], v[188:191], v[180:183], v[4:7]
	v_mfma_f32_16x16x32_bf16 v[0:3], v[196:199], v[180:183], v[0:3]
	v_mfma_f32_16x16x32_bf16 v[52:55], v[192:195], v[160:163], v[52:55]
	v_mfma_f32_16x16x32_bf16 v[48:51], v[200:203], v[160:163], v[48:51]
	v_mfma_f32_16x16x32_bf16 v[36:39], v[192:195], v[168:171], v[36:39]
	v_mfma_f32_16x16x32_bf16 v[32:35], v[200:203], v[168:171], v[32:35]
	v_mfma_f32_16x16x32_bf16 v[20:23], v[192:195], v[176:179], v[20:23]
	v_mfma_f32_16x16x32_bf16 v[16:19], v[200:203], v[176:179], v[16:19]
	v_mfma_f32_16x16x32_bf16 v[4:7], v[192:195], v[184:187], v[4:7]
	s_cmp_gt_u32 s54, 29
	s_setprio 0
	v_mfma_f32_16x16x32_bf16 v[0:3], v[200:203], v[184:187], v[0:3]
	s_barrier
	s_cbranch_scc0 .LBB0_141
	s_branch .Lpeel_done_141
; #define PG8_STAGE(bufoff, gbase, voff) do { _Pragma("unroll") for (int _i = 0; _i < 2; ++_i) \
;         __builtin_amdgcn_global_load_lds((const unsigned*)((const char*)(gbase) + (voff)[_i]), (LAS unsigned*)(lds + (bufoff) + ldsw + _i * 8192), 16, 0, 0); } while (0)
; #define PG8_LDA(dst, b, h) do { _Pragma("unroll") for (int m = 0; m < 4; ++m) _Pragma("unroll") for (int k = 0; k < 2; ++k) dst[m][k] = *(const LAS bf16x8*)(lds + PG8_SA(b, h) + aoff + m * 2048 + k * 1024); } while (0)
; #define PG8_LDB(dst, b, h) do { _Pragma("unroll") for (int n = 0; n < 2; ++n) _Pragma("unroll") for (int k = 0; k < 2; ++k) dst[n][k] = *(const LAS bf16x8*)(lds + PG8_SB(b, h) + boff + n * 2048 + k * 1024); } while (0)
; #define PG8_MMA(ai, bj, At, Bt) do { __builtin_amdgcn_s_setprio(1); _Pragma("unroll") for (int m = 0; m < 4; ++m) _Pragma("unroll") for (int n = 0; n < 2; ++n) _Pragma("unroll") for (int k = 0; k < 2; ++k) \
;         acc[ai][bj][m][n] = __builtin_amdgcn_mfma_f32_16x16x32_bf16(Bt[n][k], At[m][k], acc[ai][bj][m][n], 0, 0, 0); __builtin_amdgcn_s_setprio(0); } while (0)
; #define PG8_WAIT_L(n) asm volatile("s_waitcnt lgkmcnt(" #n ")" ::: "memory")
; #define PG8_BAR __builtin_amdgcn_s_barrier()
; #define PG8_SCHED __builtin_amdgcn_sched_barrier(0)
; template <class Epi>
; __device__ __forceinline__ void gemm_phase(LAS unsigned char* lds, const Gemm g, const StaticOrder& S, const Epi& E) {
;     ...
;             const bool last = (t == nt - 2);
;             const char* a1 = cA + (size_t)(t + 1) * kstep;
;             const char* a2 = last ? nA : cA + (size_t)(t + 2) * kstep; const char* b2 = last ? nB : cB + (size_t)(t + 2) * kstep;
;             const char* a3 = a2 + kstep; const char* b3 = b2 + kstep;
;             PG8_LDB(B0, 0, 0); PG8_SCHED; PG8_LDA(At, 0, 0); PG8_STAGE(PG8_SA(1, 1), a1 + hstepA, voffA);
;             PG8_WAIT_L(8); PG8_BAR; PG8_WAIT_L(0); PG8_MMA(0, 0, At, B0); PG8_BAR; PG8_SCHED;
;             PG8_LDB(B1, 0, 1); PG8_STAGE(PG8_SB(0, 0), b2, voffB);
;             PG8_BAR; PG8_WAIT_L(0); PG8_MMA(0, 1, At, B1); PG8_BAR;
;             PG8_LDA(At, 0, 1); PG8_STAGE(PG8_SA(0, 0), a2, voffA);
;             PG8_BAR; PG8_WAIT_L(0); PG8_MMA(1, 0, At, B0); PG8_BAR; PG8_SCHED;
.LBB0_141:
	s_add_u32 s24, s22, 0xfff84000
	s_addc_u32 s25, s23, -1
	s_cmp_eq_u32 s54, 28
	s_cselect_b32 s28, s49, s24
	s_cselect_b32 s29, s15, s25
	s_cselect_b32 s24, s50, s51
	s_cselect_b32 s25, s5, s52
	s_add_u32 s26, s28, 0x4000
	s_addc_u32 s27, s29, 0
	s_add_i32 s55, 0, 0x10000
	v_add_u32_e32 v148, s55, v134
	ds_read_b128 v[136:139], v148
	ds_read_b128 v[144:147], v148 offset:2048
	ds_read_b128 v[140:143], v148 offset:1024
	ds_read_b128 v[148:151], v148 offset:3072
	v_lshl_add_u64 v[188:189], s[22:23], 0, v[128:129]
	s_add_i32 m0, s37, 0xc000
	ds_read_b128 v[156:159], v135
	ds_read_b128 v[164:167], v135 offset:2048
	ds_read_b128 v[172:175], v135 offset:4096
	ds_read_b128 v[180:183], v135 offset:6144
	ds_read_b128 v[160:163], v135 offset:1024
	ds_read_b128 v[168:171], v135 offset:3072
	ds_read_b128 v[176:179], v135 offset:5120
	ds_read_b128 v[184:187], v135 offset:7168
	global_load_lds_dwordx4 v[188:189], off
	s_add_i32 m0, s37, 0xe000
	v_lshl_add_u64 v[188:189], s[22:23], 0, v[130:131]
	global_load_lds_dwordx4 v[188:189], off
	s_waitcnt lgkmcnt(8)
	s_barrier
	s_waitcnt lgkmcnt(7)
	v_mfma_f32_16x16x32_bf16 v[124:127], v[136:139], v[156:159], v[124:127]
	s_setprio 1
	v_mfma_f32_16x16x32_bf16 v[120:123], v[144:147], v[156:159], v[120:123]
	s_waitcnt lgkmcnt(6)
	v_mfma_f32_16x16x32_bf16 v[108:111], v[136:139], v[164:167], v[108:111]
	v_mfma_f32_16x16x32_bf16 v[104:107], v[144:147], v[164:167], v[104:107]
	s_waitcnt lgkmcnt(5)
	v_mfma_f32_16x16x32_bf16 v[92:95], v[136:139], v[172:175], v[92:95]
	v_mfma_f32_16x16x32_bf16 v[88:91], v[144:147], v[172:175], v[88:91]
	s_waitcnt lgkmcnt(4)
	v_mfma_f32_16x16x32_bf16 v[76:79], v[136:139], v[180:183], v[76:79]
	v_mfma_f32_16x16x32_bf16 v[72:75], v[144:147], v[180:183], v[72:75]
	s_waitcnt lgkmcnt(3)
	v_mfma_f32_16x16x32_bf16 v[124:127], v[140:143], v[160:163], v[124:127]
	v_mfma_f32_16x16x32_bf16 v[120:123], v[148:151], v[160:163], v[120:123]
	s_waitcnt lgkmcnt(2)
	v_mfma_f32_16x16x32_bf16 v[108:111], v[140:143], v[168:171], v[108:111]
	v_mfma_f32_16x16x32_bf16 v[104:107], v[148:151], v[168:171], v[104:107]
	s_waitcnt lgkmcnt(1)
	v_mfma_f32_16x16x32_bf16 v[92:95], v[140:143], v[176:179], v[92:95]
	v_mfma_f32_16x16x32_bf16 v[88:91], v[148:151], v[176:179], v[88:91]
	s_waitcnt lgkmcnt(0)
	v_mfma_f32_16x16x32_bf16 v[76:79], v[140:143], v[184:187], v[76:79]
	s_setprio 0
	v_mfma_f32_16x16x32_bf16 v[72:75], v[148:151], v[184:187], v[72:75]
	s_barrier
	s_add_i32 s58, 0, 0x14000
	s_add_i32 s55, s55, s36
	v_add_u32_e32 v152, s58, v134
	v_lshl_add_u64 v[204:205], s[24:25], 0, v[128:129]
	s_mov_b32 m0, s55
	ds_read_b128 v[188:191], v152
	ds_read_b128 v[196:199], v152 offset:2048
	ds_read_b128 v[192:195], v152 offset:1024
	ds_read_b128 v[200:203], v152 offset:3072
	global_load_lds_dwordx4 v[204:205], off
	s_add_i32 m0, s55, 0x2000
	v_lshl_add_u64 v[204:205], s[24:25], 0, v[130:131]
	global_load_lds_dwordx4 v[204:205], off
	s_barrier
	s_waitcnt lgkmcnt(3)
	v_mfma_f32_16x16x32_bf16 v[116:119], v[188:191], v[156:159], v[116:119]
	s_setprio 1
	s_waitcnt lgkmcnt(2)
	v_mfma_f32_16x16x32_bf16 v[112:115], v[196:199], v[156:159], v[112:115]
	s_mov_b32 m0, s37
	v_lshl_add_u64 v[204:205], s[28:29], 0, v[128:129]
	v_mfma_f32_16x16x32_bf16 v[100:103], v[188:191], v[164:167], v[100:103]
	v_mfma_f32_16x16x32_bf16 v[96:99], v[196:199], v[164:167], v[96:99]
	v_mfma_f32_16x16x32_bf16 v[84:87], v[188:191], v[172:175], v[84:87]
	v_mfma_f32_16x16x32_bf16 v[80:83], v[196:199], v[172:175], v[80:83]
	v_mfma_f32_16x16x32_bf16 v[68:71], v[188:191], v[180:183], v[68:71]
	v_mfma_f32_16x16x32_bf16 v[64:67], v[196:199], v[180:183], v[64:67]
	s_waitcnt lgkmcnt(1)
	v_mfma_f32_16x16x32_bf16 v[116:119], v[192:195], v[160:163], v[116:119]
	s_waitcnt lgkmcnt(0)
	v_mfma_f32_16x16x32_bf16 v[112:115], v[200:203], v[160:163], v[112:115]
	v_mfma_f32_16x16x32_bf16 v[100:103], v[192:195], v[168:171], v[100:103]
	v_mfma_f32_16x16x32_bf16 v[96:99], v[200:203], v[168:171], v[96:99]
	v_mfma_f32_16x16x32_bf16 v[84:87], v[192:195], v[176:179], v[84:87]
	v_mfma_f32_16x16x32_bf16 v[80:83], v[200:203], v[176:179], v[80:83]
	v_mfma_f32_16x16x32_bf16 v[68:71], v[192:195], v[184:187], v[68:71]
	s_setprio 0
	v_mfma_f32_16x16x32_bf16 v[64:67], v[200:203], v[184:187], v[64:67]
	s_barrier
	ds_read_b128 v[156:159], v135 offset:16384
	ds_read_b128 v[164:167], v135 offset:18432
	ds_read_b128 v[172:175], v135 offset:20480
	ds_read_b128 v[180:183], v135 offset:22528
	ds_read_b128 v[160:163], v135 offset:17408
	ds_read_b128 v[168:171], v135 offset:19456
	ds_read_b128 v[176:179], v135 offset:21504
	ds_read_b128 v[184:187], v135 offset:23552
	global_load_lds_dwordx4 v[204:205], off
	s_mov_b32 m0, s38
	v_lshl_add_u64 v[204:205], s[28:29], 0, v[130:131]
	global_load_lds_dwordx4 v[204:205], off
	s_barrier
	s_waitcnt lgkmcnt(7)
	v_mfma_f32_16x16x32_bf16 v[60:63], v[136:139], v[156:159], v[60:63]
	s_setprio 1
	v_mfma_f32_16x16x32_bf16 v[56:59], v[144:147], v[156:159], v[56:59]
	s_waitcnt lgkmcnt(6)
	v_mfma_f32_16x16x32_bf16 v[44:47], v[136:139], v[164:167], v[44:47]
	v_mfma_f32_16x16x32_bf16 v[40:43], v[144:147], v[164:167], v[40:43]
	s_waitcnt lgkmcnt(5)
	v_mfma_f32_16x16x32_bf16 v[28:31], v[136:139], v[172:175], v[28:31]
	v_mfma_f32_16x16x32_bf16 v[24:27], v[144:147], v[172:175], v[24:27]
	s_waitcnt lgkmcnt(4)
	v_mfma_f32_16x16x32_bf16 v[12:15], v[136:139], v[180:183], v[12:15]
	v_mfma_f32_16x16x32_bf16 v[8:11], v[144:147], v[180:183], v[8:11]
	s_waitcnt lgkmcnt(3)
	v_mfma_f32_16x16x32_bf16 v[60:63], v[140:143], v[160:163], v[60:63]
	v_mfma_f32_16x16x32_bf16 v[56:59], v[148:151], v[160:163], v[56:59]
	s_waitcnt lgkmcnt(2)
	v_mfma_f32_16x16x32_bf16 v[44:47], v[140:143], v[168:171], v[44:47]
	v_mfma_f32_16x16x32_bf16 v[40:43], v[148:151], v[168:171], v[40:43]
	s_waitcnt lgkmcnt(1)
	v_mfma_f32_16x16x32_bf16 v[28:31], v[140:143], v[176:179], v[28:31]
	v_mfma_f32_16x16x32_bf16 v[24:27], v[148:151], v[176:179], v[24:27]
	s_waitcnt lgkmcnt(0)
	v_mfma_f32_16x16x32_bf16 v[12:15], v[140:143], v[184:187], v[12:15]
	s_setprio 0
	v_mfma_f32_16x16x32_bf16 v[8:11], v[148:151], v[184:187], v[8:11]
	s_barrier
; #define PG8_STAGE(bufoff, gbase, voff) do { _Pragma("unroll") for (int _i = 0; _i < 2; ++_i) \
;         __builtin_amdgcn_global_load_lds((const unsigned*)((const char*)(gbase) + (voff)[_i]), (LAS unsigned*)(lds + (bufoff) + ldsw + _i * 8192), 16, 0, 0); } while (0)
; #define PG8_LDA(dst, b, h) do { _Pragma("unroll") for (int m = 0; m < 4; ++m) _Pragma("unroll") for (int k = 0; k < 2; ++k) dst[m][k] = *(const LAS bf16x8*)(lds + PG8_SA(b, h) + aoff + m * 2048 + k * 1024); } while (0)
; #define PG8_LDB(dst, b, h) do { _Pragma("unroll") for (int n = 0; n < 2; ++n) _Pragma("unroll") for (int k = 0; k < 2; ++k) dst[n][k] = *(const LAS bf16x8*)(lds + PG8_SB(b, h) + boff + n * 2048 + k * 1024); } while (0)
; #define PG8_MMA(ai, bj, At, Bt) do { __builtin_amdgcn_s_setprio(1); _Pragma("unroll") for (int m = 0; m < 4; ++m) _Pragma("unroll") for (int n = 0; n < 2; ++n) _Pragma("unroll") for (int k = 0; k < 2; ++k) \
;         acc[ai][bj][m][n] = __builtin_amdgcn_mfma_f32_16x16x32_bf16(Bt[n][k], At[m][k], acc[ai][bj][m][n], 0, 0, 0); __builtin_amdgcn_s_setprio(0); } while (0)
; #define PG8_WAIT_V(n) asm volatile("s_waitcnt vmcnt(" #n ")" ::: "memory")
; #define PG8_WAIT_L(n) asm volatile("s_waitcnt lgkmcnt(" #n ")" ::: "memory")
; #define PG8_BAR __builtin_amdgcn_s_barrier()
; #define PG8_SCHED __builtin_amdgcn_sched_barrier(0)
; template <class Epi>
; __device__ __forceinline__ void gemm_phase(LAS unsigned char* lds, const Gemm g, const StaticOrder& S, const Epi& E) {
;     ...
;             PG8_STAGE(PG8_SB(0, 1), b2 + hstepB, voffB);
;             PG8_WAIT_V(6); PG8_BAR; PG8_MMA(1, 1, At, B1); PG8_BAR;
;             PG8_LDB(B0, 1, 0); PG8_SCHED; PG8_LDA(At, 1, 0); PG8_STAGE(PG8_SA(0, 1), a2 + hstepA, voffA);
;             PG8_WAIT_L(8); PG8_BAR; PG8_WAIT_L(0); PG8_MMA(0, 0, At, B0); PG8_BAR; PG8_SCHED;
;             PG8_LDB(B1, 1, 1); PG8_STAGE(PG8_SB(1, 0), b3, voffB);
	s_add_u32 s56, s24, 0x80000
	s_addc_u32 s57, s25, 0
	s_add_i32 s55, s58, s36
	s_mov_b32 m0, s55
	v_lshl_add_u64 v[136:137], s[56:57], 0, v[128:129]
	global_load_lds_dwordx4 v[136:137], off
	s_add_i32 m0, s55, 0x2000
	v_lshl_add_u64 v[136:137], s[56:57], 0, v[130:131]
	global_load_lds_dwordx4 v[136:137], off
	s_waitcnt vmcnt(6)
	s_barrier
	v_mfma_f32_16x16x32_bf16 v[52:55], v[188:191], v[156:159], v[52:55]
	s_setprio 1
	v_mfma_f32_16x16x32_bf16 v[48:51], v[196:199], v[156:159], v[48:51]
	s_add_i32 s55, 0, 0x18000
	v_add_u32_e32 v148, s55, v134
	v_mfma_f32_16x16x32_bf16 v[36:39], v[188:191], v[164:167], v[36:39]
	v_mfma_f32_16x16x32_bf16 v[32:35], v[196:199], v[164:167], v[32:35]
	v_mfma_f32_16x16x32_bf16 v[20:23], v[188:191], v[172:175], v[20:23]
	v_mfma_f32_16x16x32_bf16 v[16:19], v[196:199], v[172:175], v[16:19]
	v_mfma_f32_16x16x32_bf16 v[4:7], v[188:191], v[180:183], v[4:7]
	v_mfma_f32_16x16x32_bf16 v[0:3], v[196:199], v[180:183], v[0:3]
	v_mfma_f32_16x16x32_bf16 v[52:55], v[192:195], v[160:163], v[52:55]
	v_mfma_f32_16x16x32_bf16 v[48:51], v[200:203], v[160:163], v[48:51]
	v_mfma_f32_16x16x32_bf16 v[36:39], v[192:195], v[168:171], v[36:39]
	v_mfma_f32_16x16x32_bf16 v[32:35], v[200:203], v[168:171], v[32:35]
	v_mfma_f32_16x16x32_bf16 v[20:23], v[192:195], v[176:179], v[20:23]
	v_mfma_f32_16x16x32_bf16 v[16:19], v[200:203], v[176:179], v[16:19]
	v_mfma_f32_16x16x32_bf16 v[4:7], v[192:195], v[184:187], v[4:7]
	s_setprio 0
	v_mfma_f32_16x16x32_bf16 v[0:3], v[200:203], v[184:187], v[0:3]
	s_barrier
	ds_read_b128 v[136:139], v148
	ds_read_b128 v[144:147], v148 offset:2048
	ds_read_b128 v[140:143], v148 offset:1024
	ds_read_b128 v[148:151], v148 offset:3072
	s_add_u32 s28, s28, 0x80000
	s_addc_u32 s29, s29, 0
	s_mov_b32 m0, s39
	v_lshl_add_u64 v[188:189], s[28:29], 0, v[128:129]
	ds_read_b128 v[156:159], v135 offset:32768
	ds_read_b128 v[164:167], v135 offset:34816
	ds_read_b128 v[172:175], v135 offset:36864
	ds_read_b128 v[180:183], v135 offset:38912
	ds_read_b128 v[160:163], v135 offset:33792
	ds_read_b128 v[168:171], v135 offset:35840
	ds_read_b128 v[176:179], v135 offset:37888
	ds_read_b128 v[184:187], v135 offset:39936
	global_load_lds_dwordx4 v[188:189], off
	s_mov_b32 m0, s40
	v_lshl_add_u64 v[188:189], s[28:29], 0, v[130:131]
	global_load_lds_dwordx4 v[188:189], off
	s_waitcnt lgkmcnt(8)
	s_barrier
	s_waitcnt lgkmcnt(7)
	v_mfma_f32_16x16x32_bf16 v[124:127], v[136:139], v[156:159], v[124:127]
	s_setprio 1
	v_mfma_f32_16x16x32_bf16 v[120:123], v[144:147], v[156:159], v[120:123]
	s_waitcnt lgkmcnt(6)
	v_mfma_f32_16x16x32_bf16 v[108:111], v[136:139], v[164:167], v[108:111]
	v_mfma_f32_16x16x32_bf16 v[104:107], v[144:147], v[164:167], v[104:107]
	s_waitcnt lgkmcnt(5)
	v_mfma_f32_16x16x32_bf16 v[92:95], v[136:139], v[172:175], v[92:95]
	v_mfma_f32_16x16x32_bf16 v[88:91], v[144:147], v[172:175], v[88:91]
	s_waitcnt lgkmcnt(4)
	v_mfma_f32_16x16x32_bf16 v[76:79], v[136:139], v[180:183], v[76:79]
	v_mfma_f32_16x16x32_bf16 v[72:75], v[144:147], v[180:183], v[72:75]
	s_waitcnt lgkmcnt(3)
	v_mfma_f32_16x16x32_bf16 v[124:127], v[140:143], v[160:163], v[124:127]
	v_mfma_f32_16x16x32_bf16 v[120:123], v[148:151], v[160:163], v[120:123]
	s_waitcnt lgkmcnt(2)
	v_mfma_f32_16x16x32_bf16 v[108:111], v[140:143], v[168:171], v[108:111]
	v_mfma_f32_16x16x32_bf16 v[104:107], v[148:151], v[168:171], v[104:107]
	s_waitcnt lgkmcnt(1)
	v_mfma_f32_16x16x32_bf16 v[92:95], v[140:143], v[176:179], v[92:95]
	v_mfma_f32_16x16x32_bf16 v[88:91], v[148:151], v[176:179], v[88:91]
	s_waitcnt lgkmcnt(0)
	v_mfma_f32_16x16x32_bf16 v[76:79], v[140:143], v[184:187], v[76:79]
	s_setprio 0
	v_mfma_f32_16x16x32_bf16 v[72:75], v[148:151], v[184:187], v[72:75]
	s_barrier
	s_add_i32 s56, 0, 0x1c000
	s_add_u32 s28, s24, 0x4000
	s_addc_u32 s29, s25, 0
	s_add_i32 s55, s55, s36
	v_add_u32_e32 v152, s56, v134
	v_lshl_add_u64 v[204:205], s[28:29], 0, v[128:129]
	s_mov_b32 m0, s55
	ds_read_b128 v[188:191], v152
	ds_read_b128 v[196:199], v152 offset:2048
	ds_read_b128 v[192:195], v152 offset:1024
	ds_read_b128 v[200:203], v152 offset:3072
	global_load_lds_dwordx4 v[204:205], off
	s_add_i32 m0, s55, 0x2000
	v_lshl_add_u64 v[204:205], s[28:29], 0, v[130:131]
	global_load_lds_dwordx4 v[204:205], off
	s_barrier
; #define PG8_STAGE(bufoff, gbase, voff) do { _Pragma("unroll") for (int _i = 0; _i < 2; ++_i) \
;         __builtin_amdgcn_global_load_lds((const unsigned*)((const char*)(gbase) + (voff)[_i]), (LAS unsigned*)(lds + (bufoff) + ldsw + _i * 8192), 16, 0, 0); } while (0)
; #define PG8_LDA(dst, b, h) do { _Pragma("unroll") for (int m = 0; m < 4; ++m) _Pragma("unroll") for (int k = 0; k < 2; ++k) dst[m][k] = *(const LAS bf16x8*)(lds + PG8_SA(b, h) + aoff + m * 2048 + k * 1024); } while (0)
; #define PG8_MMA(ai, bj, At, Bt) do { __builtin_amdgcn_s_setprio(1); _Pragma("unroll") for (int m = 0; m < 4; ++m) _Pragma("unroll") for (int n = 0; n < 2; ++n) _Pragma("unroll") for (int k = 0; k < 2; ++k) \
;         acc[ai][bj][m][n] = __builtin_amdgcn_mfma_f32_16x16x32_bf16(Bt[n][k], At[m][k], acc[ai][bj][m][n], 0, 0, 0); __builtin_amdgcn_s_setprio(0); } while (0)
; #define PG8_WAIT_V(n) asm volatile("s_waitcnt vmcnt(" #n ")" ::: "memory")
; #define PG8_WAIT_L(n) asm volatile("s_waitcnt lgkmcnt(" #n ")" ::: "memory")
; #define PG8_BAR __builtin_amdgcn_s_barrier()
; #define PG8_SCHED __builtin_amdgcn_sched_barrier(0)
; template <class Epi>
; __device__ __forceinline__ void gemm_phase(LAS unsigned char* lds, const Gemm g, const StaticOrder& S, const Epi& E) {
;     ...
;             PG8_BAR; PG8_WAIT_L(0); PG8_MMA(0, 1, At, B1); PG8_BAR;
;             PG8_LDA(At, 1, 1); PG8_STAGE(PG8_SA(1, 0), a3, voffA);
;             PG8_BAR; PG8_WAIT_L(0); PG8_MMA(1, 0, At, B0); PG8_BAR; PG8_SCHED;
;             PG8_STAGE(PG8_SB(1, 1), b3 + hstepB, voffB);
;             PG8_WAIT_V(6); PG8_BAR; PG8_MMA(1, 1, At, B1); PG8_BAR;
;         }
	s_waitcnt lgkmcnt(3)
	v_mfma_f32_16x16x32_bf16 v[116:119], v[188:191], v[156:159], v[116:119]
	s_setprio 1
	s_waitcnt lgkmcnt(2)
	v_mfma_f32_16x16x32_bf16 v[112:115], v[196:199], v[156:159], v[112:115]
	s_mov_b32 m0, s43
	v_lshl_add_u64 v[204:205], s[26:27], 0, v[128:129]
	v_mfma_f32_16x16x32_bf16 v[100:103], v[188:191], v[164:167], v[100:103]
	v_mfma_f32_16x16x32_bf16 v[96:99], v[196:199], v[164:167], v[96:99]
	v_mfma_f32_16x16x32_bf16 v[84:87], v[188:191], v[172:175], v[84:87]
	v_mfma_f32_16x16x32_bf16 v[80:83], v[196:199], v[172:175], v[80:83]
	v_mfma_f32_16x16x32_bf16 v[68:71], v[188:191], v[180:183], v[68:71]
	v_mfma_f32_16x16x32_bf16 v[64:67], v[196:199], v[180:183], v[64:67]
	s_waitcnt lgkmcnt(1)
	v_mfma_f32_16x16x32_bf16 v[116:119], v[192:195], v[160:163], v[116:119]
	s_waitcnt lgkmcnt(0)
	v_mfma_f32_16x16x32_bf16 v[112:115], v[200:203], v[160:163], v[112:115]
	v_mfma_f32_16x16x32_bf16 v[100:103], v[192:195], v[168:171], v[100:103]
	v_mfma_f32_16x16x32_bf16 v[96:99], v[200:203], v[168:171], v[96:99]
	v_mfma_f32_16x16x32_bf16 v[84:87], v[192:195], v[176:179], v[84:87]
	v_mfma_f32_16x16x32_bf16 v[80:83], v[200:203], v[176:179], v[80:83]
	v_mfma_f32_16x16x32_bf16 v[68:71], v[192:195], v[184:187], v[68:71]
	s_setprio 0
	v_mfma_f32_16x16x32_bf16 v[64:67], v[200:203], v[184:187], v[64:67]
	s_barrier
	ds_read_b128 v[156:159], v135 offset:49152
	ds_read_b128 v[164:167], v135 offset:51200
	ds_read_b128 v[172:175], v135 offset:53248
	ds_read_b128 v[180:183], v135 offset:55296
	ds_read_b128 v[160:163], v135 offset:50176
	ds_read_b128 v[168:171], v135 offset:52224
	ds_read_b128 v[176:179], v135 offset:54272
	ds_read_b128 v[184:187], v135 offset:56320
	global_load_lds_dwordx4 v[204:205], off
	s_mov_b32 m0, s44
	v_lshl_add_u64 v[204:205], s[26:27], 0, v[130:131]
	global_load_lds_dwordx4 v[204:205], off
	s_barrier
	s_waitcnt lgkmcnt(7)
	v_mfma_f32_16x16x32_bf16 v[60:63], v[136:139], v[156:159], v[60:63]
	s_setprio 1
	v_mfma_f32_16x16x32_bf16 v[56:59], v[144:147], v[156:159], v[56:59]
	s_waitcnt lgkmcnt(6)
	v_mfma_f32_16x16x32_bf16 v[44:47], v[136:139], v[164:167], v[44:47]
	v_mfma_f32_16x16x32_bf16 v[40:43], v[144:147], v[164:167], v[40:43]
	s_waitcnt lgkmcnt(5)
	v_mfma_f32_16x16x32_bf16 v[28:31], v[136:139], v[172:175], v[28:31]
	v_mfma_f32_16x16x32_bf16 v[24:27], v[144:147], v[172:175], v[24:27]
	s_waitcnt lgkmcnt(4)
	v_mfma_f32_16x16x32_bf16 v[12:15], v[136:139], v[180:183], v[12:15]
	v_mfma_f32_16x16x32_bf16 v[8:11], v[144:147], v[180:183], v[8:11]
	s_waitcnt lgkmcnt(3)
	v_mfma_f32_16x16x32_bf16 v[60:63], v[140:143], v[160:163], v[60:63]
	v_mfma_f32_16x16x32_bf16 v[56:59], v[148:151], v[160:163], v[56:59]
	s_waitcnt lgkmcnt(2)
	v_mfma_f32_16x16x32_bf16 v[44:47], v[140:143], v[168:171], v[44:47]
	v_mfma_f32_16x16x32_bf16 v[40:43], v[148:151], v[168:171], v[40:43]
	s_waitcnt lgkmcnt(1)
	v_mfma_f32_16x16x32_bf16 v[28:31], v[140:143], v[176:179], v[28:31]
	v_mfma_f32_16x16x32_bf16 v[24:27], v[148:151], v[176:179], v[24:27]
	s_waitcnt lgkmcnt(0)
	v_mfma_f32_16x16x32_bf16 v[12:15], v[140:143], v[184:187], v[12:15]
	s_setprio 0
	v_mfma_f32_16x16x32_bf16 v[8:11], v[148:151], v[184:187], v[8:11]
	s_barrier
	s_add_u32 s24, s24, 0x84000
	s_addc_u32 s25, s25, 0
	s_add_i32 s26, s56, s36
	s_mov_b32 m0, s26
	v_lshl_add_u64 v[136:137], s[24:25], 0, v[128:129]
	global_load_lds_dwordx4 v[136:137], off
	s_add_i32 m0, s26, 0x2000
	v_lshl_add_u64 v[136:137], s[24:25], 0, v[130:131]
	global_load_lds_dwordx4 v[136:137], off
	s_waitcnt vmcnt(6)
	s_barrier
	v_mfma_f32_16x16x32_bf16 v[52:55], v[188:191], v[156:159], v[52:55]
	s_setprio 1
	v_mfma_f32_16x16x32_bf16 v[48:51], v[196:199], v[156:159], v[48:51]
	s_add_i32 s54, s54, 2
	s_add_u32 s22, s22, 0x8000
	s_addc_u32 s23, s23, 0
	s_add_u32 s51, s51, 0x8000
	s_addc_u32 s52, s52, 0
	v_mfma_f32_16x16x32_bf16 v[36:39], v[188:191], v[164:167], v[36:39]
	v_mfma_f32_16x16x32_bf16 v[32:35], v[196:199], v[164:167], v[32:35]
	v_mfma_f32_16x16x32_bf16 v[20:23], v[188:191], v[172:175], v[20:23]
	v_mfma_f32_16x16x32_bf16 v[16:19], v[196:199], v[172:175], v[16:19]
	v_mfma_f32_16x16x32_bf16 v[4:7], v[188:191], v[180:183], v[4:7]
	v_mfma_f32_16x16x32_bf16 v[0:3], v[196:199], v[180:183], v[0:3]
	v_mfma_f32_16x16x32_bf16 v[52:55], v[192:195], v[160:163], v[52:55]
	v_mfma_f32_16x16x32_bf16 v[48:51], v[200:203], v[160:163], v[48:51]
	v_mfma_f32_16x16x32_bf16 v[36:39], v[192:195], v[168:171], v[36:39]
	v_mfma_f32_16x16x32_bf16 v[32:35], v[200:203], v[168:171], v[32:35]
	v_mfma_f32_16x16x32_bf16 v[20:23], v[192:195], v[176:179], v[20:23]
	v_mfma_f32_16x16x32_bf16 v[16:19], v[200:203], v[176:179], v[16:19]
	v_mfma_f32_16x16x32_bf16 v[4:7], v[192:195], v[184:187], v[4:7]
	s_cmp_gt_u32 s54, 29
	s_setprio 0
	v_mfma_f32_16x16x32_bf16 v[0:3], v[200:203], v[184:187], v[0:3]
	s_barrier
	s_cbranch_scc0 .LBB0_141

; #define PG8_STAGE(bufoff, gbase, voff) do { _Pragma("unroll") for (int _i = 0; _i < 2; ++_i) \
;         __builtin_amdgcn_global_load_lds((const unsigned*)((const char*)(gbase) + (voff)[_i]), (LAS unsigned*)(lds + (bufoff) + ldsw + _i * 8192), 16, 0, 0); } while (0)
; #define PG8_LDA(dst, b, h) do { _Pragma("unroll") for (int m = 0; m < 4; ++m) _Pragma("unroll") for (int k = 0; k < 2; ++k) dst[m][k] = *(const LAS bf16x8*)(lds + PG8_SA(b, h) + aoff + m * 2048 + k * 1024); } while (0)
; #define PG8_LDB(dst, b, h) do { _Pragma("unroll") for (int n = 0; n < 2; ++n) _Pragma("unroll") for (int k = 0; k < 2; ++k) dst[n][k] = *(const LAS bf16x8*)(lds + PG8_SB(b, h) + boff + n * 2048 + k * 1024); } while (0)
; #define PG8_MMA(ai, bj, At, Bt) do { __builtin_amdgcn_s_setprio(1); _Pragma("unroll") for (int m = 0; m < 4; ++m) _Pragma("unroll") for (int n = 0; n < 2; ++n) _Pragma("unroll") for (int k = 0; k < 2; ++k) \
;         acc[ai][bj][m][n] = __builtin_amdgcn_mfma_f32_16x16x32_bf16(Bt[n][k], At[m][k], acc[ai][bj][m][n], 0, 0, 0); __builtin_amdgcn_s_setprio(0); } while (0)
; #define PG8_WAIT_L(n) asm volatile("s_waitcnt lgkmcnt(" #n ")" ::: "memory")
; template <class Epi>
; __device__ __forceinline__ void gemm_phase(LAS unsigned char* lds, const Gemm g, const StaticOrder& S, const Epi& E) {
;     ...
;         const bool has_next = S.next(ui + 1, nxt);
;         const char* nA = has_next ? (const char*)g.A + (size_t)nxt.pm * tstepA : cA; const char* nB = has_next ? (const char*)g.Bt + (size_t)nxt.pn * tstepB : cB;
;         for (int t = 0; t < nt; t += 2) {
;             const bool last = (t == nt - 2);
;             const char* a1 = cA + (size_t)(t + 1) * kstep;
;             const char* a2 = last ? nA : cA + (size_t)(t + 2) * kstep; const char* b2 = last ? nB : cB + (size_t)(t + 2) * kstep;
;             const char* a3 = a2 + kstep; const char* b3 = b2 + kstep;
;             PG8_LDB(B0, 0, 0); PG8_SCHED; PG8_LDA(At, 0, 0); PG8_STAGE(PG8_SA(1, 1), a1 + hstepA, voffA);
;             PG8_WAIT_L(8); PG8_BAR; PG8_WAIT_L(0); PG8_MMA(0, 0, At, B0); PG8_BAR; PG8_SCHED;
;             PG8_LDB(B1, 0, 1); PG8_STAGE(PG8_SB(0, 0), b2, voffB);
;             PG8_BAR; PG8_WAIT_L(0); PG8_MMA(0, 1, At, B1); PG8_BAR;
;             PG8_LDA(At, 0, 1); PG8_STAGE(PG8_SA(0, 0), a2, voffA);
;             PG8_BAR; PG8_WAIT_L(0); PG8_MMA(1, 0, At, B0); PG8_BAR; PG8_SCHED;
.LBB0_186:
	s_add_u32 s4, s24, 0x4000
	s_addc_u32 s5, s25, 0
	s_add_u32 s50, s22, 0x8000
	s_addc_u32 s51, s23, 0
	s_mov_b32 s22, 0
	s_add_i32 s54, s22, 2
	s_add_u32 s23, s4, 0x4000
	s_addc_u32 s24, s5, 0
	s_cmp_eq_u32 s40, s22
	s_cselect_b32 s26, s6, s23
	s_cselect_b32 s27, s7, s24
	s_cselect_b32 s24, s20, s50
	s_cselect_b32 s25, s21, s51
	s_add_u32 s22, s26, 0x4000
	s_addc_u32 s23, s27, 0
	s_add_i32 s55, 0, 0x10000
	v_add_u32_e32 v140, s55, v207
	ds_read_b128 v[128:131], v140
	ds_read_b128 v[136:139], v140 offset:2048
	ds_read_b128 v[132:135], v140 offset:1024
	ds_read_b128 v[140:143], v140 offset:3072
	v_lshl_add_u64 v[186:187], s[4:5], 0, v[158:159]
	s_add_i32 m0, s33, 0xc000
	ds_read_b128 v[144:147], v209
	ds_read_b128 v[162:165], v209 offset:2048
	ds_read_b128 v[170:173], v209 offset:4096
	ds_read_b128 v[178:181], v209 offset:6144
	ds_read_b128 v[148:151], v209 offset:1024
	ds_read_b128 v[166:169], v209 offset:3072
	ds_read_b128 v[174:177], v209 offset:5120
	ds_read_b128 v[182:185], v209 offset:7168
	global_load_lds_dwordx4 v[186:187], off
	s_add_i32 m0, s33, 0xe000
	v_lshl_add_u64 v[186:187], s[4:5], 0, v[160:161]
	global_load_lds_dwordx4 v[186:187], off
	s_waitcnt lgkmcnt(8)
	s_barrier
	s_waitcnt lgkmcnt(7)
	v_mfma_f32_16x16x32_bf16 v[124:127], v[128:131], v[144:147], 0
	s_setprio 1
	v_mfma_f32_16x16x32_bf16 v[120:123], v[136:139], v[144:147], 0
	s_waitcnt lgkmcnt(6)
	v_mfma_f32_16x16x32_bf16 v[116:119], v[128:131], v[162:165], 0
	v_mfma_f32_16x16x32_bf16 v[112:115], v[136:139], v[162:165], 0
	s_waitcnt lgkmcnt(5)
	v_mfma_f32_16x16x32_bf16 v[108:111], v[128:131], v[170:173], 0
	v_mfma_f32_16x16x32_bf16 v[104:107], v[136:139], v[170:173], 0
	s_waitcnt lgkmcnt(4)
	v_mfma_f32_16x16x32_bf16 v[100:103], v[128:131], v[178:181], 0
	v_mfma_f32_16x16x32_bf16 v[96:99], v[136:139], v[178:181], 0
	s_waitcnt lgkmcnt(3)
	v_mfma_f32_16x16x32_bf16 v[124:127], v[132:135], v[148:151], v[124:127]
	v_mfma_f32_16x16x32_bf16 v[120:123], v[140:143], v[148:151], v[120:123]
	s_waitcnt lgkmcnt(2)
	v_mfma_f32_16x16x32_bf16 v[116:119], v[132:135], v[166:169], v[116:119]
	v_mfma_f32_16x16x32_bf16 v[112:115], v[140:143], v[166:169], v[112:115]
	s_waitcnt lgkmcnt(1)
	v_mfma_f32_16x16x32_bf16 v[108:111], v[132:135], v[174:177], v[108:111]
	v_mfma_f32_16x16x32_bf16 v[104:107], v[140:143], v[174:177], v[104:107]
	s_waitcnt lgkmcnt(0)
	v_mfma_f32_16x16x32_bf16 v[100:103], v[132:135], v[182:185], v[100:103]
	s_setprio 0
	v_mfma_f32_16x16x32_bf16 v[96:99], v[140:143], v[182:185], v[96:99]
	s_barrier
	s_add_i32 s58, 0, 0x14000
	s_add_i32 s55, s55, s31
	v_add_u32_e32 v198, s58, v207
	v_lshl_add_u64 v[202:203], s[24:25], 0, v[152:153]
	s_mov_b32 m0, s55
	ds_read_b128 v[186:189], v198
	ds_read_b128 v[194:197], v198 offset:2048
	ds_read_b128 v[190:193], v198 offset:1024
	ds_read_b128 v[198:201], v198 offset:3072
	global_load_lds_dwordx4 v[202:203], off
	s_add_i32 m0, s55, 0x2000
	v_lshl_add_u64 v[202:203], s[24:25], 0, v[156:157]
	global_load_lds_dwordx4 v[202:203], off
	s_barrier
	s_waitcnt lgkmcnt(3)
	v_mfma_f32_16x16x32_bf16 v[92:95], v[186:189], v[144:147], 0
	s_setprio 1
	s_waitcnt lgkmcnt(2)
	v_mfma_f32_16x16x32_bf16 v[88:91], v[194:197], v[144:147], 0
	s_mov_b32 m0, s33
	v_lshl_add_u64 v[202:203], s[26:27], 0, v[152:153]
	v_mfma_f32_16x16x32_bf16 v[84:87], v[186:189], v[162:165], 0
	v_mfma_f32_16x16x32_bf16 v[80:83], v[194:197], v[162:165], 0
	v_mfma_f32_16x16x32_bf16 v[76:79], v[186:189], v[170:173], 0
	v_mfma_f32_16x16x32_bf16 v[72:75], v[194:197], v[170:173], 0
	v_mfma_f32_16x16x32_bf16 v[68:71], v[186:189], v[178:181], 0
	v_mfma_f32_16x16x32_bf16 v[64:67], v[194:197], v[178:181], 0
	s_waitcnt lgkmcnt(1)
	v_mfma_f32_16x16x32_bf16 v[92:95], v[190:193], v[148:151], v[92:95]
	s_waitcnt lgkmcnt(0)
	v_mfma_f32_16x16x32_bf16 v[88:91], v[198:201], v[148:151], v[88:91]
	v_mfma_f32_16x16x32_bf16 v[84:87], v[190:193], v[166:169], v[84:87]
	v_mfma_f32_16x16x32_bf16 v[80:83], v[198:201], v[166:169], v[80:83]
	v_mfma_f32_16x16x32_bf16 v[76:79], v[190:193], v[174:177], v[76:79]
	v_mfma_f32_16x16x32_bf16 v[72:75], v[198:201], v[174:177], v[72:75]
	v_mfma_f32_16x16x32_bf16 v[68:71], v[190:193], v[182:185], v[68:71]
	s_setprio 0
	v_mfma_f32_16x16x32_bf16 v[64:67], v[198:201], v[182:185], v[64:67]
	s_barrier
	ds_read_b128 v[144:147], v209 offset:16384
	ds_read_b128 v[162:165], v209 offset:18432
	ds_read_b128 v[170:173], v209 offset:20480
	ds_read_b128 v[178:181], v209 offset:22528
	ds_read_b128 v[148:151], v209 offset:17408
	ds_read_b128 v[166:169], v209 offset:19456
	ds_read_b128 v[174:177], v209 offset:21504
	ds_read_b128 v[182:185], v209 offset:23552
	global_load_lds_dwordx4 v[202:203], off
	s_mov_b32 m0, s34
	v_lshl_add_u64 v[202:203], s[26:27], 0, v[156:157]
	global_load_lds_dwordx4 v[202:203], off
	s_barrier
	s_waitcnt lgkmcnt(7)
	v_mfma_f32_16x16x32_bf16 v[60:63], v[128:131], v[144:147], 0
	s_setprio 1
	v_mfma_f32_16x16x32_bf16 v[56:59], v[136:139], v[144:147], 0
	s_waitcnt lgkmcnt(6)
	v_mfma_f32_16x16x32_bf16 v[52:55], v[128:131], v[162:165], 0
	v_mfma_f32_16x16x32_bf16 v[48:51], v[136:139], v[162:165], 0
	s_waitcnt lgkmcnt(5)
	v_mfma_f32_16x16x32_bf16 v[44:47], v[128:131], v[170:173], 0
	v_mfma_f32_16x16x32_bf16 v[40:43], v[136:139], v[170:173], 0
	s_waitcnt lgkmcnt(4)
	v_mfma_f32_16x16x32_bf16 v[36:39], v[128:131], v[178:181], 0
	v_mfma_f32_16x16x32_bf16 v[32:35], v[136:139], v[178:181], 0
	s_waitcnt lgkmcnt(3)
	v_mfma_f32_16x16x32_bf16 v[60:63], v[132:135], v[148:151], v[60:63]
	v_mfma_f32_16x16x32_bf16 v[56:59], v[140:143], v[148:151], v[56:59]
	s_waitcnt lgkmcnt(2)
	v_mfma_f32_16x16x32_bf16 v[52:55], v[132:135], v[166:169], v[52:55]
	v_mfma_f32_16x16x32_bf16 v[48:51], v[140:143], v[166:169], v[48:51]
	s_waitcnt lgkmcnt(1)
	v_mfma_f32_16x16x32_bf16 v[44:47], v[132:135], v[174:177], v[44:47]
	v_mfma_f32_16x16x32_bf16 v[40:43], v[140:143], v[174:177], v[40:43]
	s_waitcnt lgkmcnt(0)
	v_mfma_f32_16x16x32_bf16 v[36:39], v[132:135], v[182:185], v[36:39]
	s_setprio 0
	v_mfma_f32_16x16x32_bf16 v[32:35], v[140:143], v[182:185], v[32:35]
	s_barrier
; #define PG8_STAGE(bufoff, gbase, voff) do { _Pragma("unroll") for (int _i = 0; _i < 2; ++_i) \
;         __builtin_amdgcn_global_load_lds((const unsigned*)((const char*)(gbase) + (voff)[_i]), (LAS unsigned*)(lds + (bufoff) + ldsw + _i * 8192), 16, 0, 0); } while (0)
; #define PG8_LDA(dst, b, h) do { _Pragma("unroll") for (int m = 0; m < 4; ++m) _Pragma("unroll") for (int k = 0; k < 2; ++k) dst[m][k] = *(const LAS bf16x8*)(lds + PG8_SA(b, h) + aoff + m * 2048 + k * 1024); } while (0)
; #define PG8_LDB(dst, b, h) do { _Pragma("unroll") for (int n = 0; n < 2; ++n) _Pragma("unroll") for (int k = 0; k < 2; ++k) dst[n][k] = *(const LAS bf16x8*)(lds + PG8_SB(b, h) + boff + n * 2048 + k * 1024); } while (0)
; #define PG8_MMA(ai, bj, At, Bt) do { __builtin_amdgcn_s_setprio(1); _Pragma("unroll") for (int m = 0; m < 4; ++m) _Pragma("unroll") for (int n = 0; n < 2; ++n) _Pragma("unroll") for (int k = 0; k < 2; ++k) \
;         acc[ai][bj][m][n] = __builtin_amdgcn_mfma_f32_16x16x32_bf16(Bt[n][k], At[m][k], acc[ai][bj][m][n], 0, 0, 0); __builtin_amdgcn_s_setprio(0); } while (0)
; #define PG8_WAIT_V(n) asm volatile("s_waitcnt vmcnt(" #n ")" ::: "memory")
; #define PG8_WAIT_L(n) asm volatile("s_waitcnt lgkmcnt(" #n ")" ::: "memory")
; #define PG8_BAR __builtin_amdgcn_s_barrier()
; #define PG8_SCHED __builtin_amdgcn_sched_barrier(0)
; template <class Epi>
; __device__ __forceinline__ void gemm_phase(LAS unsigned char* lds, const Gemm g, const StaticOrder& S, const Epi& E) {
;     ...
;             PG8_STAGE(PG8_SB(0, 1), b2 + hstepB, voffB);
;             PG8_WAIT_V(6); PG8_BAR; PG8_MMA(1, 1, At, B1); PG8_BAR;
;             PG8_LDB(B0, 1, 0); PG8_SCHED; PG8_LDA(At, 1, 0); PG8_STAGE(PG8_SA(0, 1), a2 + hstepA, voffA);
;             PG8_WAIT_L(8); PG8_BAR; PG8_WAIT_L(0); PG8_MMA(0, 0, At, B0); PG8_BAR; PG8_SCHED;
;             PG8_LDB(B1, 1, 1); PG8_STAGE(PG8_SB(1, 0), b3, voffB);
;             PG8_BAR; PG8_WAIT_L(0); PG8_MMA(0, 1, At, B1); PG8_BAR;
	s_add_u32 s56, s24, s52
	s_addc_u32 s57, s25, 0
	s_add_i32 s55, s58, s31
	s_mov_b32 m0, s55
	v_lshl_add_u64 v[128:129], s[56:57], 0, v[152:153]
	global_load_lds_dwordx4 v[128:129], off
	s_add_i32 m0, s55, 0x2000
	v_lshl_add_u64 v[128:129], s[56:57], 0, v[156:157]
	global_load_lds_dwordx4 v[128:129], off
	s_waitcnt vmcnt(6)
	s_barrier
	v_mfma_f32_16x16x32_bf16 v[28:31], v[186:189], v[144:147], 0
	s_setprio 1
	v_mfma_f32_16x16x32_bf16 v[24:27], v[194:197], v[144:147], 0
	s_add_i32 s55, 0, 0x18000
	v_add_u32_e32 v140, s55, v207
	v_mfma_f32_16x16x32_bf16 v[20:23], v[186:189], v[162:165], 0
	v_mfma_f32_16x16x32_bf16 v[16:19], v[194:197], v[162:165], 0
	v_mfma_f32_16x16x32_bf16 v[12:15], v[186:189], v[170:173], 0
	v_mfma_f32_16x16x32_bf16 v[8:11], v[194:197], v[170:173], 0
	v_mfma_f32_16x16x32_bf16 v[4:7], v[186:189], v[178:181], 0
	v_mfma_f32_16x16x32_bf16 v[0:3], v[194:197], v[178:181], 0
	v_mfma_f32_16x16x32_bf16 v[28:31], v[190:193], v[148:151], v[28:31]
	v_mfma_f32_16x16x32_bf16 v[24:27], v[198:201], v[148:151], v[24:27]
	v_mfma_f32_16x16x32_bf16 v[20:23], v[190:193], v[166:169], v[20:23]
	v_mfma_f32_16x16x32_bf16 v[16:19], v[198:201], v[166:169], v[16:19]
	v_mfma_f32_16x16x32_bf16 v[12:15], v[190:193], v[174:177], v[12:15]
	v_mfma_f32_16x16x32_bf16 v[8:11], v[198:201], v[174:177], v[8:11]
	v_mfma_f32_16x16x32_bf16 v[4:7], v[190:193], v[182:185], v[4:7]
	s_setprio 0
	v_mfma_f32_16x16x32_bf16 v[0:3], v[198:201], v[182:185], v[0:3]
	s_barrier
	ds_read_b128 v[128:131], v140
	ds_read_b128 v[136:139], v140 offset:2048
	ds_read_b128 v[132:135], v140 offset:1024
	ds_read_b128 v[140:143], v140 offset:3072
	s_add_u32 s26, s26, s52
	s_addc_u32 s27, s27, 0
	s_mov_b32 m0, s35
	v_lshl_add_u64 v[186:187], s[26:27], 0, v[152:153]
	ds_read_b128 v[144:147], v209 offset:32768
	ds_read_b128 v[162:165], v209 offset:34816
	ds_read_b128 v[170:173], v209 offset:36864
	ds_read_b128 v[178:181], v209 offset:38912
	ds_read_b128 v[148:151], v209 offset:33792
	ds_read_b128 v[166:169], v209 offset:35840
	ds_read_b128 v[174:177], v209 offset:37888
	ds_read_b128 v[182:185], v209 offset:39936
	global_load_lds_dwordx4 v[186:187], off
	s_mov_b32 m0, s36
	v_lshl_add_u64 v[186:187], s[26:27], 0, v[156:157]
	global_load_lds_dwordx4 v[186:187], off
	s_waitcnt lgkmcnt(8)
	s_barrier
	s_waitcnt lgkmcnt(7)
	v_mfma_f32_16x16x32_bf16 v[124:127], v[128:131], v[144:147], v[124:127]
	s_setprio 1
	v_mfma_f32_16x16x32_bf16 v[120:123], v[136:139], v[144:147], v[120:123]
	s_waitcnt lgkmcnt(6)
	v_mfma_f32_16x16x32_bf16 v[116:119], v[128:131], v[162:165], v[116:119]
	v_mfma_f32_16x16x32_bf16 v[112:115], v[136:139], v[162:165], v[112:115]
	s_waitcnt lgkmcnt(5)
	v_mfma_f32_16x16x32_bf16 v[108:111], v[128:131], v[170:173], v[108:111]
	v_mfma_f32_16x16x32_bf16 v[104:107], v[136:139], v[170:173], v[104:107]
	s_waitcnt lgkmcnt(4)
	v_mfma_f32_16x16x32_bf16 v[100:103], v[128:131], v[178:181], v[100:103]
	v_mfma_f32_16x16x32_bf16 v[96:99], v[136:139], v[178:181], v[96:99]
	s_waitcnt lgkmcnt(3)
	v_mfma_f32_16x16x32_bf16 v[124:127], v[132:135], v[148:151], v[124:127]
	v_mfma_f32_16x16x32_bf16 v[120:123], v[140:143], v[148:151], v[120:123]
	s_waitcnt lgkmcnt(2)
	v_mfma_f32_16x16x32_bf16 v[116:119], v[132:135], v[166:169], v[116:119]
	v_mfma_f32_16x16x32_bf16 v[112:115], v[140:143], v[166:169], v[112:115]
	s_waitcnt lgkmcnt(1)
	v_mfma_f32_16x16x32_bf16 v[108:111], v[132:135], v[174:177], v[108:111]
	v_mfma_f32_16x16x32_bf16 v[104:107], v[140:143], v[174:177], v[104:107]
	s_waitcnt lgkmcnt(0)
	v_mfma_f32_16x16x32_bf16 v[100:103], v[132:135], v[182:185], v[100:103]
	s_setprio 0
	v_mfma_f32_16x16x32_bf16 v[96:99], v[140:143], v[182:185], v[96:99]
	s_barrier
	s_add_i32 s26, 0, 0x1c000
	s_add_u32 s24, s24, 0x4000
	s_addc_u32 s25, s25, 0
	s_add_i32 s27, s55, s31
	v_add_u32_e32 v198, s26, v207
	v_lshl_add_u64 v[202:203], s[24:25], 0, v[152:153]
	s_mov_b32 m0, s27
	ds_read_b128 v[186:189], v198
	ds_read_b128 v[194:197], v198 offset:2048
	ds_read_b128 v[190:193], v198 offset:1024
	ds_read_b128 v[198:201], v198 offset:3072
	global_load_lds_dwordx4 v[202:203], off
	s_add_i32 m0, s27, 0x2000
	v_lshl_add_u64 v[202:203], s[24:25], 0, v[156:157]
	global_load_lds_dwordx4 v[202:203], off
	s_barrier
	s_waitcnt lgkmcnt(3)
	v_mfma_f32_16x16x32_bf16 v[92:95], v[186:189], v[144:147], v[92:95]
	s_setprio 1
	s_waitcnt lgkmcnt(2)
	v_mfma_f32_16x16x32_bf16 v[88:91], v[194:197], v[144:147], v[88:91]
	s_mov_b32 m0, s38
	v_lshl_add_u64 v[202:203], s[22:23], 0, v[152:153]
	v_mfma_f32_16x16x32_bf16 v[84:87], v[186:189], v[162:165], v[84:87]
	v_mfma_f32_16x16x32_bf16 v[80:83], v[194:197], v[162:165], v[80:83]
	v_mfma_f32_16x16x32_bf16 v[76:79], v[186:189], v[170:173], v[76:79]
	v_mfma_f32_16x16x32_bf16 v[72:75], v[194:197], v[170:173], v[72:75]
	v_mfma_f32_16x16x32_bf16 v[68:71], v[186:189], v[178:181], v[68:71]
	v_mfma_f32_16x16x32_bf16 v[64:67], v[194:197], v[178:181], v[64:67]
	s_waitcnt lgkmcnt(1)
	v_mfma_f32_16x16x32_bf16 v[92:95], v[190:193], v[148:151], v[92:95]
	s_waitcnt lgkmcnt(0)
	v_mfma_f32_16x16x32_bf16 v[88:91], v[198:201], v[148:151], v[88:91]
	v_mfma_f32_16x16x32_bf16 v[84:87], v[190:193], v[166:169], v[84:87]
	v_mfma_f32_16x16x32_bf16 v[80:83], v[198:201], v[166:169], v[80:83]
	v_mfma_f32_16x16x32_bf16 v[76:79], v[190:193], v[174:177], v[76:79]
	v_mfma_f32_16x16x32_bf16 v[72:75], v[198:201], v[174:177], v[72:75]
	v_mfma_f32_16x16x32_bf16 v[68:71], v[190:193], v[182:185], v[68:71]
	s_setprio 0
	v_mfma_f32_16x16x32_bf16 v[64:67], v[198:201], v[182:185], v[64:67]
	s_barrier
; #define PG8_STAGE(bufoff, gbase, voff) do { _Pragma("unroll") for (int _i = 0; _i < 2; ++_i) \
;         __builtin_amdgcn_global_load_lds((const unsigned*)((const char*)(gbase) + (voff)[_i]), (LAS unsigned*)(lds + (bufoff) + ldsw + _i * 8192), 16, 0, 0); } while (0)
; #define PG8_LDA(dst, b, h) do { _Pragma("unroll") for (int m = 0; m < 4; ++m) _Pragma("unroll") for (int k = 0; k < 2; ++k) dst[m][k] = *(const LAS bf16x8*)(lds + PG8_SA(b, h) + aoff + m * 2048 + k * 1024); } while (0)
; #define PG8_LDB(dst, b, h) do { _Pragma("unroll") for (int n = 0; n < 2; ++n) _Pragma("unroll") for (int k = 0; k < 2; ++k) dst[n][k] = *(const LAS bf16x8*)(lds + PG8_SB(b, h) + boff + n * 2048 + k * 1024); } while (0)
; #define PG8_MMA(ai, bj, At, Bt) do { __builtin_amdgcn_s_setprio(1); _Pragma("unroll") for (int m = 0; m < 4; ++m) _Pragma("unroll") for (int n = 0; n < 2; ++n) _Pragma("unroll") for (int k = 0; k < 2; ++k) \
;         acc[ai][bj][m][n] = __builtin_amdgcn_mfma_f32_16x16x32_bf16(Bt[n][k], At[m][k], acc[ai][bj][m][n], 0, 0, 0); __builtin_amdgcn_s_setprio(0); } while (0)
; #define PG8_WAIT_V(n) asm volatile("s_waitcnt vmcnt(" #n ")" ::: "memory")
; #define PG8_WAIT_L(n) asm volatile("s_waitcnt lgkmcnt(" #n ")" ::: "memory")
; #define PG8_BAR __builtin_amdgcn_s_barrier()
; #define PG8_SCHED __builtin_amdgcn_sched_barrier(0)
; template <class Epi>
; __device__ __forceinline__ void gemm_phase(LAS unsigned char* lds, const Gemm g, const StaticOrder& S, const Epi& E) {
;     ...
;             const bool last = (t == nt - 2);
;             const char* a1 = cA + (size_t)(t + 1) * kstep;
;             const char* a2 = last ? nA : cA + (size_t)(t + 2) * kstep; const char* b2 = last ? nB : cB + (size_t)(t + 2) * kstep;
;             const char* a3 = a2 + kstep; const char* b3 = b2 + kstep;
;             PG8_LDB(B0, 0, 0); PG8_SCHED; PG8_LDA(At, 0, 0); PG8_STAGE(PG8_SA(1, 1), a1 + hstepA, voffA);
;             PG8_WAIT_L(8); PG8_BAR; PG8_WAIT_L(0); PG8_MMA(0, 0, At, B0); PG8_BAR; PG8_SCHED;
;     ...
;             PG8_LDA(At, 1, 1); PG8_STAGE(PG8_SA(1, 0), a3, voffA);
;             PG8_BAR; PG8_WAIT_L(0); PG8_MMA(1, 0, At, B0); PG8_BAR; PG8_SCHED;
;             PG8_STAGE(PG8_SB(1, 1), b3 + hstepB, voffB);
;             PG8_WAIT_V(6); PG8_BAR; PG8_MMA(1, 1, At, B1); PG8_BAR;
;         }
	ds_read_b128 v[144:147], v209 offset:49152
	ds_read_b128 v[162:165], v209 offset:51200
	ds_read_b128 v[170:173], v209 offset:53248
	ds_read_b128 v[178:181], v209 offset:55296
	ds_read_b128 v[148:151], v209 offset:50176
	ds_read_b128 v[166:169], v209 offset:52224
	ds_read_b128 v[174:177], v209 offset:54272
	ds_read_b128 v[182:185], v209 offset:56320
	global_load_lds_dwordx4 v[202:203], off
	s_mov_b32 m0, s39
	v_lshl_add_u64 v[202:203], s[22:23], 0, v[156:157]
	global_load_lds_dwordx4 v[202:203], off
	s_barrier
	s_waitcnt lgkmcnt(7)
	v_mfma_f32_16x16x32_bf16 v[60:63], v[128:131], v[144:147], v[60:63]
	s_setprio 1
	v_mfma_f32_16x16x32_bf16 v[56:59], v[136:139], v[144:147], v[56:59]
	s_waitcnt lgkmcnt(6)
	v_mfma_f32_16x16x32_bf16 v[52:55], v[128:131], v[162:165], v[52:55]
	v_mfma_f32_16x16x32_bf16 v[48:51], v[136:139], v[162:165], v[48:51]
	s_waitcnt lgkmcnt(5)
	v_mfma_f32_16x16x32_bf16 v[44:47], v[128:131], v[170:173], v[44:47]
	v_mfma_f32_16x16x32_bf16 v[40:43], v[136:139], v[170:173], v[40:43]
	s_waitcnt lgkmcnt(4)
	v_mfma_f32_16x16x32_bf16 v[36:39], v[128:131], v[178:181], v[36:39]
	v_mfma_f32_16x16x32_bf16 v[32:35], v[136:139], v[178:181], v[32:35]
	s_waitcnt lgkmcnt(3)
	v_mfma_f32_16x16x32_bf16 v[60:63], v[132:135], v[148:151], v[60:63]
	v_mfma_f32_16x16x32_bf16 v[56:59], v[140:143], v[148:151], v[56:59]
	s_waitcnt lgkmcnt(2)
	v_mfma_f32_16x16x32_bf16 v[52:55], v[132:135], v[166:169], v[52:55]
	v_mfma_f32_16x16x32_bf16 v[48:51], v[140:143], v[166:169], v[48:51]
	s_waitcnt lgkmcnt(1)
	v_mfma_f32_16x16x32_bf16 v[44:47], v[132:135], v[174:177], v[44:47]
	v_mfma_f32_16x16x32_bf16 v[40:43], v[140:143], v[174:177], v[40:43]
	s_waitcnt lgkmcnt(0)
	v_mfma_f32_16x16x32_bf16 v[36:39], v[132:135], v[182:185], v[36:39]
	s_setprio 0
	v_mfma_f32_16x16x32_bf16 v[32:35], v[140:143], v[182:185], v[32:35]
	s_barrier
	s_add_u32 s22, s24, s52
	s_addc_u32 s23, s25, 0
	s_add_i32 s24, s26, s31
	s_mov_b32 m0, s24
	v_lshl_add_u64 v[128:129], s[22:23], 0, v[152:153]
	global_load_lds_dwordx4 v[128:129], off
	s_add_i32 m0, s24, 0x2000
	v_lshl_add_u64 v[128:129], s[22:23], 0, v[156:157]
	global_load_lds_dwordx4 v[128:129], off
	s_waitcnt vmcnt(6)
	s_barrier
	v_mfma_f32_16x16x32_bf16 v[28:31], v[186:189], v[144:147], v[28:31]
	s_setprio 1
	v_mfma_f32_16x16x32_bf16 v[24:27], v[194:197], v[144:147], v[24:27]
	s_add_u32 s4, s4, 0x8000
	s_addc_u32 s5, s5, 0
	s_add_u32 s50, s50, 0x8000
	s_addc_u32 s51, s51, 0
	v_mfma_f32_16x16x32_bf16 v[20:23], v[186:189], v[162:165], v[20:23]
	v_mfma_f32_16x16x32_bf16 v[16:19], v[194:197], v[162:165], v[16:19]
	v_mfma_f32_16x16x32_bf16 v[12:15], v[186:189], v[170:173], v[12:15]
	v_mfma_f32_16x16x32_bf16 v[8:11], v[194:197], v[170:173], v[8:11]
	v_mfma_f32_16x16x32_bf16 v[4:7], v[186:189], v[178:181], v[4:7]
	v_mfma_f32_16x16x32_bf16 v[0:3], v[194:197], v[178:181], v[0:3]
	v_mfma_f32_16x16x32_bf16 v[28:31], v[190:193], v[148:151], v[28:31]
	v_mfma_f32_16x16x32_bf16 v[24:27], v[198:201], v[148:151], v[24:27]
	v_mfma_f32_16x16x32_bf16 v[20:23], v[190:193], v[166:169], v[20:23]
	v_mfma_f32_16x16x32_bf16 v[16:19], v[198:201], v[166:169], v[16:19]
	v_mfma_f32_16x16x32_bf16 v[12:15], v[190:193], v[174:177], v[12:15]
	v_mfma_f32_16x16x32_bf16 v[8:11], v[198:201], v[174:177], v[8:11]
	v_mfma_f32_16x16x32_bf16 v[4:7], v[190:193], v[182:185], v[4:7]
	s_cmp_ge_u32 s54, s28
	s_mov_b32 s22, s54
	s_setprio 0
	v_mfma_f32_16x16x32_bf16 v[0:3], v[198:201], v[182:185], v[0:3]
	s_barrier
	s_cbranch_scc0 .LBB0_187
	s_branch .Lpeel_done_187
.LBB0_187:
	s_add_i32 s54, s22, 2
	s_add_u32 s23, s4, 0x4000
	s_addc_u32 s24, s5, 0
	s_cmp_eq_u32 s40, s22
	s_cselect_b32 s26, s6, s23
	s_cselect_b32 s27, s7, s24
	s_cselect_b32 s24, s20, s50
	s_cselect_b32 s25, s21, s51
	s_add_u32 s22, s26, 0x4000
	s_addc_u32 s23, s27, 0
	s_add_i32 s55, 0, 0x10000
	v_add_u32_e32 v140, s55, v207
	ds_read_b128 v[128:131], v140
	ds_read_b128 v[136:139], v140 offset:2048
	ds_read_b128 v[132:135], v140 offset:1024
	ds_read_b128 v[140:143], v140 offset:3072
	v_lshl_add_u64 v[186:187], s[4:5], 0, v[158:159]
	s_add_i32 m0, s33, 0xc000
	ds_read_b128 v[144:147], v209
	ds_read_b128 v[162:165], v209 offset:2048
	ds_read_b128 v[170:173], v209 offset:4096
	ds_read_b128 v[178:181], v209 offset:6144
	ds_read_b128 v[148:151], v209 offset:1024
	ds_read_b128 v[166:169], v209 offset:3072
	ds_read_b128 v[174:177], v209 offset:5120
	ds_read_b128 v[182:185], v209 offset:7168
	global_load_lds_dwordx4 v[186:187], off
	s_add_i32 m0, s33, 0xe000
	v_lshl_add_u64 v[186:187], s[4:5], 0, v[160:161]
	global_load_lds_dwordx4 v[186:187], off
	s_waitcnt lgkmcnt(8)
	s_barrier
	s_waitcnt lgkmcnt(7)
	v_mfma_f32_16x16x32_bf16 v[124:127], v[128:131], v[144:147], v[124:127]
	s_setprio 1
	v_mfma_f32_16x16x32_bf16 v[120:123], v[136:139], v[144:147], v[120:123]
	s_waitcnt lgkmcnt(6)
	v_mfma_f32_16x16x32_bf16 v[116:119], v[128:131], v[162:165], v[116:119]
	v_mfma_f32_16x16x32_bf16 v[112:115], v[136:139], v[162:165], v[112:115]
	s_waitcnt lgkmcnt(5)
	v_mfma_f32_16x16x32_bf16 v[108:111], v[128:131], v[170:173], v[108:111]
	v_mfma_f32_16x16x32_bf16 v[104:107], v[136:139], v[170:173], v[104:107]
	s_waitcnt lgkmcnt(4)
	v_mfma_f32_16x16x32_bf16 v[100:103], v[128:131], v[178:181], v[100:103]
	v_mfma_f32_16x16x32_bf16 v[96:99], v[136:139], v[178:181], v[96:99]
	s_waitcnt lgkmcnt(3)
	v_mfma_f32_16x16x32_bf16 v[124:127], v[132:135], v[148:151], v[124:127]
	v_mfma_f32_16x16x32_bf16 v[120:123], v[140:143], v[148:151], v[120:123]
	s_waitcnt lgkmcnt(2)
	v_mfma_f32_16x16x32_bf16 v[116:119], v[132:135], v[166:169], v[116:119]
	v_mfma_f32_16x16x32_bf16 v[112:115], v[140:143], v[166:169], v[112:115]
	s_waitcnt lgkmcnt(1)
	v_mfma_f32_16x16x32_bf16 v[108:111], v[132:135], v[174:177], v[108:111]
	v_mfma_f32_16x16x32_bf16 v[104:107], v[140:143], v[174:177], v[104:107]
	s_waitcnt lgkmcnt(0)
	v_mfma_f32_16x16x32_bf16 v[100:103], v[132:135], v[182:185], v[100:103]
	s_setprio 0
	v_mfma_f32_16x16x32_bf16 v[96:99], v[140:143], v[182:185], v[96:99]
	s_barrier
; #define PG8_STAGE(bufoff, gbase, voff) do { _Pragma("unroll") for (int _i = 0; _i < 2; ++_i) \
;         __builtin_amdgcn_global_load_lds((const unsigned*)((const char*)(gbase) + (voff)[_i]), (LAS unsigned*)(lds + (bufoff) + ldsw + _i * 8192), 16, 0, 0); } while (0)
; #define PG8_LDA(dst, b, h) do { _Pragma("unroll") for (int m = 0; m < 4; ++m) _Pragma("unroll") for (int k = 0; k < 2; ++k) dst[m][k] = *(const LAS bf16x8*)(lds + PG8_SA(b, h) + aoff + m * 2048 + k * 1024); } while (0)
; #define PG8_LDB(dst, b, h) do { _Pragma("unroll") for (int n = 0; n < 2; ++n) _Pragma("unroll") for (int k = 0; k < 2; ++k) dst[n][k] = *(const LAS bf16x8*)(lds + PG8_SB(b, h) + boff + n * 2048 + k * 1024); } while (0)
; #define PG8_MMA(ai, bj, At, Bt) do { __builtin_amdgcn_s_setprio(1); _Pragma("unroll") for (int m = 0; m < 4; ++m) _Pragma("unroll") for (int n = 0; n < 2; ++n) _Pragma("unroll") for (int k = 0; k < 2; ++k) \
;         acc[ai][bj][m][n] = __builtin_amdgcn_mfma_f32_16x16x32_bf16(Bt[n][k], At[m][k], acc[ai][bj][m][n], 0, 0, 0); __builtin_amdgcn_s_setprio(0); } while (0)
; #define PG8_WAIT_V(n) asm volatile("s_waitcnt vmcnt(" #n ")" ::: "memory")
; #define PG8_WAIT_L(n) asm volatile("s_waitcnt lgkmcnt(" #n ")" ::: "memory")
; #define PG8_BAR __builtin_amdgcn_s_barrier()
; #define PG8_SCHED __builtin_amdgcn_sched_barrier(0)
; template <class Epi>
; __device__ __forceinline__ void gemm_phase(LAS unsigned char* lds, const Gemm g, const StaticOrder& S, const Epi& E) {
;     ...
;             PG8_LDB(B1, 0, 1); PG8_STAGE(PG8_SB(0, 0), b2, voffB);
;             PG8_BAR; PG8_WAIT_L(0); PG8_MMA(0, 1, At, B1); PG8_BAR;
;             PG8_LDA(At, 0, 1); PG8_STAGE(PG8_SA(0, 0), a2, voffA);
;             PG8_BAR; PG8_WAIT_L(0); PG8_MMA(1, 0, At, B0); PG8_BAR; PG8_SCHED;
;             PG8_STAGE(PG8_SB(0, 1), b2 + hstepB, voffB);
;             PG8_WAIT_V(6); PG8_BAR; PG8_MMA(1, 1, At, B1); PG8_BAR;
;             PG8_LDB(B0, 1, 0); PG8_SCHED; PG8_LDA(At, 1, 0); PG8_STAGE(PG8_SA(0, 1), a2 + hstepA, voffA);
	s_add_i32 s58, 0, 0x14000
	s_add_i32 s55, s55, s31
	v_add_u32_e32 v198, s58, v207
	v_lshl_add_u64 v[202:203], s[24:25], 0, v[152:153]
	s_mov_b32 m0, s55
	ds_read_b128 v[186:189], v198
	ds_read_b128 v[194:197], v198 offset:2048
	ds_read_b128 v[190:193], v198 offset:1024
	ds_read_b128 v[198:201], v198 offset:3072
	global_load_lds_dwordx4 v[202:203], off
	s_add_i32 m0, s55, 0x2000
	v_lshl_add_u64 v[202:203], s[24:25], 0, v[156:157]
	global_load_lds_dwordx4 v[202:203], off
	s_barrier
	s_waitcnt lgkmcnt(3)
	v_mfma_f32_16x16x32_bf16 v[92:95], v[186:189], v[144:147], v[92:95]
	s_setprio 1
	s_waitcnt lgkmcnt(2)
	v_mfma_f32_16x16x32_bf16 v[88:91], v[194:197], v[144:147], v[88:91]
	s_mov_b32 m0, s33
	v_lshl_add_u64 v[202:203], s[26:27], 0, v[152:153]
	v_mfma_f32_16x16x32_bf16 v[84:87], v[186:189], v[162:165], v[84:87]
	v_mfma_f32_16x16x32_bf16 v[80:83], v[194:197], v[162:165], v[80:83]
	v_mfma_f32_16x16x32_bf16 v[76:79], v[186:189], v[170:173], v[76:79]
	v_mfma_f32_16x16x32_bf16 v[72:75], v[194:197], v[170:173], v[72:75]
	v_mfma_f32_16x16x32_bf16 v[68:71], v[186:189], v[178:181], v[68:71]
	v_mfma_f32_16x16x32_bf16 v[64:67], v[194:197], v[178:181], v[64:67]
	s_waitcnt lgkmcnt(1)
	v_mfma_f32_16x16x32_bf16 v[92:95], v[190:193], v[148:151], v[92:95]
	s_waitcnt lgkmcnt(0)
	v_mfma_f32_16x16x32_bf16 v[88:91], v[198:201], v[148:151], v[88:91]
	v_mfma_f32_16x16x32_bf16 v[84:87], v[190:193], v[166:169], v[84:87]
	v_mfma_f32_16x16x32_bf16 v[80:83], v[198:201], v[166:169], v[80:83]
	v_mfma_f32_16x16x32_bf16 v[76:79], v[190:193], v[174:177], v[76:79]
	v_mfma_f32_16x16x32_bf16 v[72:75], v[198:201], v[174:177], v[72:75]
	v_mfma_f32_16x16x32_bf16 v[68:71], v[190:193], v[182:185], v[68:71]
	s_setprio 0
	v_mfma_f32_16x16x32_bf16 v[64:67], v[198:201], v[182:185], v[64:67]
	s_barrier
	ds_read_b128 v[144:147], v209 offset:16384
	ds_read_b128 v[162:165], v209 offset:18432
	ds_read_b128 v[170:173], v209 offset:20480
	ds_read_b128 v[178:181], v209 offset:22528
	ds_read_b128 v[148:151], v209 offset:17408
	ds_read_b128 v[166:169], v209 offset:19456
	ds_read_b128 v[174:177], v209 offset:21504
	ds_read_b128 v[182:185], v209 offset:23552
	global_load_lds_dwordx4 v[202:203], off
	s_mov_b32 m0, s34
	v_lshl_add_u64 v[202:203], s[26:27], 0, v[156:157]
	global_load_lds_dwordx4 v[202:203], off
	s_barrier
	s_waitcnt lgkmcnt(7)
	v_mfma_f32_16x16x32_bf16 v[60:63], v[128:131], v[144:147], v[60:63]
	s_setprio 1
	v_mfma_f32_16x16x32_bf16 v[56:59], v[136:139], v[144:147], v[56:59]
	s_waitcnt lgkmcnt(6)
	v_mfma_f32_16x16x32_bf16 v[52:55], v[128:131], v[162:165], v[52:55]
	v_mfma_f32_16x16x32_bf16 v[48:51], v[136:139], v[162:165], v[48:51]
	s_waitcnt lgkmcnt(5)
	v_mfma_f32_16x16x32_bf16 v[44:47], v[128:131], v[170:173], v[44:47]
	v_mfma_f32_16x16x32_bf16 v[40:43], v[136:139], v[170:173], v[40:43]
	s_waitcnt lgkmcnt(4)
	v_mfma_f32_16x16x32_bf16 v[36:39], v[128:131], v[178:181], v[36:39]
	v_mfma_f32_16x16x32_bf16 v[32:35], v[136:139], v[178:181], v[32:35]
	s_waitcnt lgkmcnt(3)
	v_mfma_f32_16x16x32_bf16 v[60:63], v[132:135], v[148:151], v[60:63]
	v_mfma_f32_16x16x32_bf16 v[56:59], v[140:143], v[148:151], v[56:59]
	s_waitcnt lgkmcnt(2)
	v_mfma_f32_16x16x32_bf16 v[52:55], v[132:135], v[166:169], v[52:55]
	v_mfma_f32_16x16x32_bf16 v[48:51], v[140:143], v[166:169], v[48:51]
	s_waitcnt lgkmcnt(1)
	v_mfma_f32_16x16x32_bf16 v[44:47], v[132:135], v[174:177], v[44:47]
	v_mfma_f32_16x16x32_bf16 v[40:43], v[140:143], v[174:177], v[40:43]
	s_waitcnt lgkmcnt(0)
	v_mfma_f32_16x16x32_bf16 v[36:39], v[132:135], v[182:185], v[36:39]
	s_setprio 0
	v_mfma_f32_16x16x32_bf16 v[32:35], v[140:143], v[182:185], v[32:35]
	s_barrier
	s_add_u32 s56, s24, s52
	s_addc_u32 s57, s25, 0
	s_add_i32 s55, s58, s31
	s_mov_b32 m0, s55
	v_lshl_add_u64 v[128:129], s[56:57], 0, v[152:153]
	global_load_lds_dwordx4 v[128:129], off
	s_add_i32 m0, s55, 0x2000
	v_lshl_add_u64 v[128:129], s[56:57], 0, v[156:157]
	global_load_lds_dwordx4 v[128:129], off
	s_waitcnt vmcnt(6)
	s_barrier
	v_mfma_f32_16x16x32_bf16 v[28:31], v[186:189], v[144:147], v[28:31]
	s_setprio 1
	v_mfma_f32_16x16x32_bf16 v[24:27], v[194:197], v[144:147], v[24:27]
	s_add_i32 s55, 0, 0x18000
	v_add_u32_e32 v140, s55, v207
	v_mfma_f32_16x16x32_bf16 v[20:23], v[186:189], v[162:165], v[20:23]
	v_mfma_f32_16x16x32_bf16 v[16:19], v[194:197], v[162:165], v[16:19]
	v_mfma_f32_16x16x32_bf16 v[12:15], v[186:189], v[170:173], v[12:15]
	v_mfma_f32_16x16x32_bf16 v[8:11], v[194:197], v[170:173], v[8:11]
	v_mfma_f32_16x16x32_bf16 v[4:7], v[186:189], v[178:181], v[4:7]
	v_mfma_f32_16x16x32_bf16 v[0:3], v[194:197], v[178:181], v[0:3]
	v_mfma_f32_16x16x32_bf16 v[28:31], v[190:193], v[148:151], v[28:31]
	v_mfma_f32_16x16x32_bf16 v[24:27], v[198:201], v[148:151], v[24:27]
	v_mfma_f32_16x16x32_bf16 v[20:23], v[190:193], v[166:169], v[20:23]
	v_mfma_f32_16x16x32_bf16 v[16:19], v[198:201], v[166:169], v[16:19]
	v_mfma_f32_16x16x32_bf16 v[12:15], v[190:193], v[174:177], v[12:15]
	v_mfma_f32_16x16x32_bf16 v[8:11], v[198:201], v[174:177], v[8:11]
	v_mfma_f32_16x16x32_bf16 v[4:7], v[190:193], v[182:185], v[4:7]
	s_setprio 0
	v_mfma_f32_16x16x32_bf16 v[0:3], v[198:201], v[182:185], v[0:3]
	s_barrier
	ds_read_b128 v[128:131], v140
	ds_read_b128 v[136:139], v140 offset:2048
	ds_read_b128 v[132:135], v140 offset:1024
	ds_read_b128 v[140:143], v140 offset:3072
	s_add_u32 s26, s26, s52
	s_addc_u32 s27, s27, 0
	s_mov_b32 m0, s35
	v_lshl_add_u64 v[186:187], s[26:27], 0, v[152:153]
	ds_read_b128 v[144:147], v209 offset:32768
	ds_read_b128 v[162:165], v209 offset:34816
	ds_read_b128 v[170:173], v209 offset:36864
	ds_read_b128 v[178:181], v209 offset:38912
	ds_read_b128 v[148:151], v209 offset:33792
	ds_read_b128 v[166:169], v209 offset:35840
	ds_read_b128 v[174:177], v209 offset:37888
	ds_read_b128 v[182:185], v209 offset:39936
	global_load_lds_dwordx4 v[186:187], off
	s_mov_b32 m0, s36
	v_lshl_add_u64 v[186:187], s[26:27], 0, v[156:157]
	global_load_lds_dwordx4 v[186:187], off
	s_waitcnt lgkmcnt(8)
	s_barrier
; #define PG8_STAGE(bufoff, gbase, voff) do { _Pragma("unroll") for (int _i = 0; _i < 2; ++_i) \
;         __builtin_amdgcn_global_load_lds((const unsigned*)((const char*)(gbase) + (voff)[_i]), (LAS unsigned*)(lds + (bufoff) + ldsw + _i * 8192), 16, 0, 0); } while (0)
; #define PG8_LDA(dst, b, h) do { _Pragma("unroll") for (int m = 0; m < 4; ++m) _Pragma("unroll") for (int k = 0; k < 2; ++k) dst[m][k] = *(const LAS bf16x8*)(lds + PG8_SA(b, h) + aoff + m * 2048 + k * 1024); } while (0)
; #define PG8_LDB(dst, b, h) do { _Pragma("unroll") for (int n = 0; n < 2; ++n) _Pragma("unroll") for (int k = 0; k < 2; ++k) dst[n][k] = *(const LAS bf16x8*)(lds + PG8_SB(b, h) + boff + n * 2048 + k * 1024); } while (0)
; #define PG8_MMA(ai, bj, At, Bt) do { __builtin_amdgcn_s_setprio(1); _Pragma("unroll") for (int m = 0; m < 4; ++m) _Pragma("unroll") for (int n = 0; n < 2; ++n) _Pragma("unroll") for (int k = 0; k < 2; ++k) \
;         acc[ai][bj][m][n] = __builtin_amdgcn_mfma_f32_16x16x32_bf16(Bt[n][k], At[m][k], acc[ai][bj][m][n], 0, 0, 0); __builtin_amdgcn_s_setprio(0); } while (0)
; #define PG8_WAIT_V(n) asm volatile("s_waitcnt vmcnt(" #n ")" ::: "memory")
; #define PG8_WAIT_L(n) asm volatile("s_waitcnt lgkmcnt(" #n ")" ::: "memory")
; #define PG8_BAR __builtin_amdgcn_s_barrier()
; #define PG8_SCHED __builtin_amdgcn_sched_barrier(0)
; template <class Epi>
; __device__ __forceinline__ void gemm_phase(LAS unsigned char* lds, const Gemm g, const StaticOrder& S, const Epi& E) {
;     ...
;             PG8_WAIT_L(8); PG8_BAR; PG8_WAIT_L(0); PG8_MMA(0, 0, At, B0); PG8_BAR; PG8_SCHED;
;             PG8_LDB(B1, 1, 1); PG8_STAGE(PG8_SB(1, 0), b3, voffB);
;             PG8_BAR; PG8_WAIT_L(0); PG8_MMA(0, 1, At, B1); PG8_BAR;
;             PG8_LDA(At, 1, 1); PG8_STAGE(PG8_SA(1, 0), a3, voffA);
;             PG8_BAR; PG8_WAIT_L(0); PG8_MMA(1, 0, At, B0); PG8_BAR; PG8_SCHED;
;             PG8_STAGE(PG8_SB(1, 1), b3 + hstepB, voffB);
;             PG8_WAIT_V(6); PG8_BAR; PG8_MMA(1, 1, At, B1); PG8_BAR;
;         }
	s_waitcnt lgkmcnt(7)
	v_mfma_f32_16x16x32_bf16 v[124:127], v[128:131], v[144:147], v[124:127]
	s_setprio 1
	v_mfma_f32_16x16x32_bf16 v[120:123], v[136:139], v[144:147], v[120:123]
	s_waitcnt lgkmcnt(6)
	v_mfma_f32_16x16x32_bf16 v[116:119], v[128:131], v[162:165], v[116:119]
	v_mfma_f32_16x16x32_bf16 v[112:115], v[136:139], v[162:165], v[112:115]
	s_waitcnt lgkmcnt(5)
	v_mfma_f32_16x16x32_bf16 v[108:111], v[128:131], v[170:173], v[108:111]
	v_mfma_f32_16x16x32_bf16 v[104:107], v[136:139], v[170:173], v[104:107]
	s_waitcnt lgkmcnt(4)
	v_mfma_f32_16x16x32_bf16 v[100:103], v[128:131], v[178:181], v[100:103]
	v_mfma_f32_16x16x32_bf16 v[96:99], v[136:139], v[178:181], v[96:99]
	s_waitcnt lgkmcnt(3)
	v_mfma_f32_16x16x32_bf16 v[124:127], v[132:135], v[148:151], v[124:127]
	v_mfma_f32_16x16x32_bf16 v[120:123], v[140:143], v[148:151], v[120:123]
	s_waitcnt lgkmcnt(2)
	v_mfma_f32_16x16x32_bf16 v[116:119], v[132:135], v[166:169], v[116:119]
	v_mfma_f32_16x16x32_bf16 v[112:115], v[140:143], v[166:169], v[112:115]
	s_waitcnt lgkmcnt(1)
	v_mfma_f32_16x16x32_bf16 v[108:111], v[132:135], v[174:177], v[108:111]
	v_mfma_f32_16x16x32_bf16 v[104:107], v[140:143], v[174:177], v[104:107]
	s_waitcnt lgkmcnt(0)
	v_mfma_f32_16x16x32_bf16 v[100:103], v[132:135], v[182:185], v[100:103]
	s_setprio 0
	v_mfma_f32_16x16x32_bf16 v[96:99], v[140:143], v[182:185], v[96:99]
	s_barrier
	s_add_i32 s26, 0, 0x1c000
	s_add_u32 s24, s24, 0x4000
	s_addc_u32 s25, s25, 0
	s_add_i32 s27, s55, s31
	v_add_u32_e32 v198, s26, v207
	v_lshl_add_u64 v[202:203], s[24:25], 0, v[152:153]
	s_mov_b32 m0, s27
	ds_read_b128 v[186:189], v198
	ds_read_b128 v[194:197], v198 offset:2048
	ds_read_b128 v[190:193], v198 offset:1024
	ds_read_b128 v[198:201], v198 offset:3072
	global_load_lds_dwordx4 v[202:203], off
	s_add_i32 m0, s27, 0x2000
	v_lshl_add_u64 v[202:203], s[24:25], 0, v[156:157]
	global_load_lds_dwordx4 v[202:203], off
	s_barrier
	s_waitcnt lgkmcnt(3)
	v_mfma_f32_16x16x32_bf16 v[92:95], v[186:189], v[144:147], v[92:95]
	s_setprio 1
	s_waitcnt lgkmcnt(2)
	v_mfma_f32_16x16x32_bf16 v[88:91], v[194:197], v[144:147], v[88:91]
	s_mov_b32 m0, s38
	v_lshl_add_u64 v[202:203], s[22:23], 0, v[152:153]
	v_mfma_f32_16x16x32_bf16 v[84:87], v[186:189], v[162:165], v[84:87]
	v_mfma_f32_16x16x32_bf16 v[80:83], v[194:197], v[162:165], v[80:83]
	v_mfma_f32_16x16x32_bf16 v[76:79], v[186:189], v[170:173], v[76:79]
	v_mfma_f32_16x16x32_bf16 v[72:75], v[194:197], v[170:173], v[72:75]
	v_mfma_f32_16x16x32_bf16 v[68:71], v[186:189], v[178:181], v[68:71]
	v_mfma_f32_16x16x32_bf16 v[64:67], v[194:197], v[178:181], v[64:67]
	s_waitcnt lgkmcnt(1)
	v_mfma_f32_16x16x32_bf16 v[92:95], v[190:193], v[148:151], v[92:95]
	s_waitcnt lgkmcnt(0)
	v_mfma_f32_16x16x32_bf16 v[88:91], v[198:201], v[148:151], v[88:91]
	v_mfma_f32_16x16x32_bf16 v[84:87], v[190:193], v[166:169], v[84:87]
	v_mfma_f32_16x16x32_bf16 v[80:83], v[198:201], v[166:169], v[80:83]
	v_mfma_f32_16x16x32_bf16 v[76:79], v[190:193], v[174:177], v[76:79]
	v_mfma_f32_16x16x32_bf16 v[72:75], v[198:201], v[174:177], v[72:75]
	v_mfma_f32_16x16x32_bf16 v[68:71], v[190:193], v[182:185], v[68:71]
	s_setprio 0
	v_mfma_f32_16x16x32_bf16 v[64:67], v[198:201], v[182:185], v[64:67]
	s_barrier
	ds_read_b128 v[144:147], v209 offset:49152
	ds_read_b128 v[162:165], v209 offset:51200
	ds_read_b128 v[170:173], v209 offset:53248
	ds_read_b128 v[178:181], v209 offset:55296
	ds_read_b128 v[148:151], v209 offset:50176
	ds_read_b128 v[166:169], v209 offset:52224
	ds_read_b128 v[174:177], v209 offset:54272
	ds_read_b128 v[182:185], v209 offset:56320
	global_load_lds_dwordx4 v[202:203], off
	s_mov_b32 m0, s39
	v_lshl_add_u64 v[202:203], s[22:23], 0, v[156:157]
	global_load_lds_dwordx4 v[202:203], off
	s_barrier
	s_waitcnt lgkmcnt(7)
	v_mfma_f32_16x16x32_bf16 v[60:63], v[128:131], v[144:147], v[60:63]
	s_setprio 1
	v_mfma_f32_16x16x32_bf16 v[56:59], v[136:139], v[144:147], v[56:59]
	s_waitcnt lgkmcnt(6)
	v_mfma_f32_16x16x32_bf16 v[52:55], v[128:131], v[162:165], v[52:55]
	v_mfma_f32_16x16x32_bf16 v[48:51], v[136:139], v[162:165], v[48:51]
	s_waitcnt lgkmcnt(5)
	v_mfma_f32_16x16x32_bf16 v[44:47], v[128:131], v[170:173], v[44:47]
	v_mfma_f32_16x16x32_bf16 v[40:43], v[136:139], v[170:173], v[40:43]
	s_waitcnt lgkmcnt(4)
	v_mfma_f32_16x16x32_bf16 v[36:39], v[128:131], v[178:181], v[36:39]
	v_mfma_f32_16x16x32_bf16 v[32:35], v[136:139], v[178:181], v[32:35]
	s_waitcnt lgkmcnt(3)
	v_mfma_f32_16x16x32_bf16 v[60:63], v[132:135], v[148:151], v[60:63]
	v_mfma_f32_16x16x32_bf16 v[56:59], v[140:143], v[148:151], v[56:59]
	s_waitcnt lgkmcnt(2)
	v_mfma_f32_16x16x32_bf16 v[52:55], v[132:135], v[166:169], v[52:55]
	v_mfma_f32_16x16x32_bf16 v[48:51], v[140:143], v[166:169], v[48:51]
	s_waitcnt lgkmcnt(1)
	v_mfma_f32_16x16x32_bf16 v[44:47], v[132:135], v[174:177], v[44:47]
	v_mfma_f32_16x16x32_bf16 v[40:43], v[140:143], v[174:177], v[40:43]
	s_waitcnt lgkmcnt(0)
	v_mfma_f32_16x16x32_bf16 v[36:39], v[132:135], v[182:185], v[36:39]
	s_setprio 0
	v_mfma_f32_16x16x32_bf16 v[32:35], v[140:143], v[182:185], v[32:35]
	s_barrier
	s_add_u32 s22, s24, s52
	s_addc_u32 s23, s25, 0
	s_add_i32 s24, s26, s31
	s_mov_b32 m0, s24
	v_lshl_add_u64 v[128:129], s[22:23], 0, v[152:153]
	global_load_lds_dwordx4 v[128:129], off
	s_add_i32 m0, s24, 0x2000
	v_lshl_add_u64 v[128:129], s[22:23], 0, v[156:157]
	global_load_lds_dwordx4 v[128:129], off
	s_waitcnt vmcnt(6)
	s_barrier
	v_mfma_f32_16x16x32_bf16 v[28:31], v[186:189], v[144:147], v[28:31]
	s_setprio 1
	v_mfma_f32_16x16x32_bf16 v[24:27], v[194:197], v[144:147], v[24:27]
	s_add_u32 s4, s4, 0x8000
	s_addc_u32 s5, s5, 0
	s_add_u32 s50, s50, 0x8000
	s_addc_u32 s51, s51, 0
	v_mfma_f32_16x16x32_bf16 v[20:23], v[186:189], v[162:165], v[20:23]
	v_mfma_f32_16x16x32_bf16 v[16:19], v[194:197], v[162:165], v[16:19]
	v_mfma_f32_16x16x32_bf16 v[12:15], v[186:189], v[170:173], v[12:15]
	v_mfma_f32_16x16x32_bf16 v[8:11], v[194:197], v[170:173], v[8:11]
	v_mfma_f32_16x16x32_bf16 v[4:7], v[186:189], v[178:181], v[4:7]
	v_mfma_f32_16x16x32_bf16 v[0:3], v[194:197], v[178:181], v[0:3]
	v_mfma_f32_16x16x32_bf16 v[28:31], v[190:193], v[148:151], v[28:31]
	v_mfma_f32_16x16x32_bf16 v[24:27], v[198:201], v[148:151], v[24:27]
	v_mfma_f32_16x16x32_bf16 v[20:23], v[190:193], v[166:169], v[20:23]
	v_mfma_f32_16x16x32_bf16 v[16:19], v[198:201], v[166:169], v[16:19]
	v_mfma_f32_16x16x32_bf16 v[12:15], v[190:193], v[174:177], v[12:15]
	v_mfma_f32_16x16x32_bf16 v[8:11], v[198:201], v[174:177], v[8:11]
	v_mfma_f32_16x16x32_bf16 v[4:7], v[190:193], v[182:185], v[4:7]
	s_cmp_ge_u32 s54, s28
	s_mov_b32 s22, s54
	s_setprio 0
	v_mfma_f32_16x16x32_bf16 v[0:3], v[198:201], v[182:185], v[0:3]
	s_barrier
	s_cbranch_scc0 .LBB0_187

; #define PG8_STAGE(bufoff, gbase, voff) do { _Pragma("unroll") for (int _i = 0; _i < 2; ++_i) \
;         __builtin_amdgcn_global_load_lds((const unsigned*)((const char*)(gbase) + (voff)[_i]), (LAS unsigned*)(lds + (bufoff) + ldsw + _i * 8192), 16, 0, 0); } while (0)
; #define PG8_LDA(dst, b, h) do { _Pragma("unroll") for (int m = 0; m < 4; ++m) _Pragma("unroll") for (int k = 0; k < 2; ++k) dst[m][k] = *(const LAS bf16x8*)(lds + PG8_SA(b, h) + aoff + m * 2048 + k * 1024); } while (0)
; #define PG8_LDB(dst, b, h) do { _Pragma("unroll") for (int n = 0; n < 2; ++n) _Pragma("unroll") for (int k = 0; k < 2; ++k) dst[n][k] = *(const LAS bf16x8*)(lds + PG8_SB(b, h) + boff + n * 2048 + k * 1024); } while (0)
; #define PG8_MMA(ai, bj, At, Bt) do { __builtin_amdgcn_s_setprio(1); _Pragma("unroll") for (int m = 0; m < 4; ++m) _Pragma("unroll") for (int n = 0; n < 2; ++n) _Pragma("unroll") for (int k = 0; k < 2; ++k) \
;         acc[ai][bj][m][n] = __builtin_amdgcn_mfma_f32_16x16x32_bf16(Bt[n][k], At[m][k], acc[ai][bj][m][n], 0, 0, 0); __builtin_amdgcn_s_setprio(0); } while (0)
; #define PG8_WAIT_L(n) asm volatile("s_waitcnt lgkmcnt(" #n ")" ::: "memory")
; template <class Epi>
; __device__ __forceinline__ void gemm_phase(LAS unsigned char* lds, const Gemm g, const StaticOrder& S, const Epi& E) {
;     ...
;         const bool has_next = S.next(ui + 1, nxt);
;         const char* nA = has_next ? (const char*)g.A + (size_t)nxt.pm * tstepA : cA; const char* nB = has_next ? (const char*)g.Bt + (size_t)nxt.pn * tstepB : cB;
;         for (int t = 0; t < nt; t += 2) {
;             const bool last = (t == nt - 2);
;             const char* a1 = cA + (size_t)(t + 1) * kstep;
;             const char* a2 = last ? nA : cA + (size_t)(t + 2) * kstep; const char* b2 = last ? nB : cB + (size_t)(t + 2) * kstep;
;             const char* a3 = a2 + kstep; const char* b3 = b2 + kstep;
;             PG8_LDB(B0, 0, 0); PG8_SCHED; PG8_LDA(At, 0, 0); PG8_STAGE(PG8_SA(1, 1), a1 + hstepA, voffA);
;             PG8_WAIT_L(8); PG8_BAR; PG8_WAIT_L(0); PG8_MMA(0, 0, At, B0); PG8_BAR; PG8_SCHED;
;             PG8_LDB(B1, 0, 1); PG8_STAGE(PG8_SB(0, 0), b2, voffB);
;             PG8_BAR; PG8_WAIT_L(0); PG8_MMA(0, 1, At, B1); PG8_BAR;
;             PG8_LDA(At, 0, 1); PG8_STAGE(PG8_SA(0, 0), a2, voffA);
;             PG8_BAR; PG8_WAIT_L(0); PG8_MMA(1, 0, At, B0); PG8_BAR; PG8_SCHED;
.LBB0_246:
	s_ashr_i32 s5, s4, 31
	v_cmp_lt_i64_e32 vcc, s[6:7], v[154:155]
	s_lshl_b64 s[6:7], s[4:5], 20
	v_readlane_b32 s8, v252, 53
	v_readlane_b32 s9, v252, 54
	s_add_u32 s6, s8, s6
	s_addc_u32 s7, s9, s7
	s_and_b64 s[8:9], vcc, exec
	s_cselect_b32 s5, s7, s13
	s_cselect_b32 s11, s6, s12
	s_ashr_i32 s3, s2, 31
	s_lshl_b64 s[8:9], s[2:3], 20
	s_add_u32 s8, s21, s8
	s_addc_u32 s9, s22, s9
	s_and_b64 s[16:17], vcc, exec
	s_cselect_b32 s3, s9, s15
	s_cselect_b32 s35, s8, s14
	s_add_u32 s12, s12, 0x84000
	s_addc_u32 s13, s13, 0
	s_add_u32 s36, s14, 0x8000
	s_addc_u32 s37, s15, 0
	s_mov_b32 s38, -2
	s_add_u32 s14, s12, 0xfff84000
	s_addc_u32 s15, s13, -1
	s_cmp_eq_u32 s38, 28
	s_cselect_b32 s18, s11, s14
	s_cselect_b32 s19, s5, s15
	s_cselect_b32 s14, s35, s36
	s_cselect_b32 s15, s3, s37
	s_add_u32 s16, s18, 0x4000
	s_addc_u32 s17, s19, 0
	s_add_i32 s39, 0, 0x10000
	v_add_u32_e32 v140, s39, v170
	ds_read_b128 v[128:131], v140
	ds_read_b128 v[136:139], v140 offset:2048
	ds_read_b128 v[132:135], v140 offset:1024
	ds_read_b128 v[140:143], v140 offset:3072
	v_lshl_add_u64 v[194:195], s[12:13], 0, v[156:157]
	s_add_i32 m0, s25, 0xc000
	ds_read_b128 v[144:147], v172
	ds_read_b128 v[166:169], v172 offset:2048
	ds_read_b128 v[178:181], v172 offset:4096
	ds_read_b128 v[186:189], v172 offset:6144
	ds_read_b128 v[148:151], v172 offset:1024
	ds_read_b128 v[174:177], v172 offset:3072
	ds_read_b128 v[182:185], v172 offset:5120
	ds_read_b128 v[190:193], v172 offset:7168
	global_load_lds_dwordx4 v[194:195], off
	s_add_i32 m0, s25, 0xe000
	v_lshl_add_u64 v[194:195], s[12:13], 0, v[158:159]
	global_load_lds_dwordx4 v[194:195], off
	s_waitcnt lgkmcnt(8)
	s_barrier
	s_waitcnt lgkmcnt(7)
	v_mfma_f32_16x16x32_bf16 v[124:127], v[128:131], v[144:147], 0
	s_setprio 1
	v_mfma_f32_16x16x32_bf16 v[120:123], v[136:139], v[144:147], 0
	s_waitcnt lgkmcnt(6)
	v_mfma_f32_16x16x32_bf16 v[108:111], v[128:131], v[166:169], 0
	v_mfma_f32_16x16x32_bf16 v[104:107], v[136:139], v[166:169], 0
	s_waitcnt lgkmcnt(5)
	v_mfma_f32_16x16x32_bf16 v[92:95], v[128:131], v[178:181], 0
	v_mfma_f32_16x16x32_bf16 v[88:91], v[136:139], v[178:181], 0
	s_waitcnt lgkmcnt(4)
	v_mfma_f32_16x16x32_bf16 v[76:79], v[128:131], v[186:189], 0
	v_mfma_f32_16x16x32_bf16 v[72:75], v[136:139], v[186:189], 0
	s_waitcnt lgkmcnt(3)
	v_mfma_f32_16x16x32_bf16 v[124:127], v[132:135], v[148:151], v[124:127]
	v_mfma_f32_16x16x32_bf16 v[120:123], v[140:143], v[148:151], v[120:123]
	s_waitcnt lgkmcnt(2)
	v_mfma_f32_16x16x32_bf16 v[108:111], v[132:135], v[174:177], v[108:111]
	v_mfma_f32_16x16x32_bf16 v[104:107], v[140:143], v[174:177], v[104:107]
	s_waitcnt lgkmcnt(1)
	v_mfma_f32_16x16x32_bf16 v[92:95], v[132:135], v[182:185], v[92:95]
	v_mfma_f32_16x16x32_bf16 v[88:91], v[140:143], v[182:185], v[88:91]
	s_waitcnt lgkmcnt(0)
	v_mfma_f32_16x16x32_bf16 v[76:79], v[132:135], v[190:193], v[76:79]
	s_setprio 0
	v_mfma_f32_16x16x32_bf16 v[72:75], v[140:143], v[190:193], v[72:75]
	s_barrier
	s_add_i32 s42, 0, 0x14000
	s_add_i32 s39, s39, s23
	v_add_u32_e32 v152, s42, v170
	v_lshl_add_u64 v[210:211], s[14:15], 0, v[156:157]
	s_mov_b32 m0, s39
	ds_read_b128 v[194:197], v152
	ds_read_b128 v[202:205], v152 offset:2048
	ds_read_b128 v[198:201], v152 offset:1024
	ds_read_b128 v[206:209], v152 offset:3072
	global_load_lds_dwordx4 v[210:211], off
	s_add_i32 m0, s39, 0x2000
	v_lshl_add_u64 v[210:211], s[14:15], 0, v[158:159]
	global_load_lds_dwordx4 v[210:211], off
	s_barrier
	s_waitcnt lgkmcnt(3)
	v_mfma_f32_16x16x32_bf16 v[116:119], v[194:197], v[144:147], 0
	s_setprio 1
	s_waitcnt lgkmcnt(2)
	v_mfma_f32_16x16x32_bf16 v[112:115], v[202:205], v[144:147], 0
	s_mov_b32 m0, s25
	v_lshl_add_u64 v[210:211], s[18:19], 0, v[156:157]
	v_mfma_f32_16x16x32_bf16 v[100:103], v[194:197], v[166:169], 0
	v_mfma_f32_16x16x32_bf16 v[96:99], v[202:205], v[166:169], 0
	v_mfma_f32_16x16x32_bf16 v[84:87], v[194:197], v[178:181], 0
	v_mfma_f32_16x16x32_bf16 v[80:83], v[202:205], v[178:181], 0
	v_mfma_f32_16x16x32_bf16 v[68:71], v[194:197], v[186:189], 0
	v_mfma_f32_16x16x32_bf16 v[64:67], v[202:205], v[186:189], 0
	s_waitcnt lgkmcnt(1)
	v_mfma_f32_16x16x32_bf16 v[116:119], v[198:201], v[148:151], v[116:119]
	s_waitcnt lgkmcnt(0)
	v_mfma_f32_16x16x32_bf16 v[112:115], v[206:209], v[148:151], v[112:115]
	v_mfma_f32_16x16x32_bf16 v[100:103], v[198:201], v[174:177], v[100:103]
	v_mfma_f32_16x16x32_bf16 v[96:99], v[206:209], v[174:177], v[96:99]
	v_mfma_f32_16x16x32_bf16 v[84:87], v[198:201], v[182:185], v[84:87]
	v_mfma_f32_16x16x32_bf16 v[80:83], v[206:209], v[182:185], v[80:83]
	v_mfma_f32_16x16x32_bf16 v[68:71], v[198:201], v[190:193], v[68:71]
	s_setprio 0
	v_mfma_f32_16x16x32_bf16 v[64:67], v[206:209], v[190:193], v[64:67]
	s_barrier
	ds_read_b128 v[144:147], v172 offset:16384
	ds_read_b128 v[166:169], v172 offset:18432
	ds_read_b128 v[178:181], v172 offset:20480
	ds_read_b128 v[186:189], v172 offset:22528
	ds_read_b128 v[148:151], v172 offset:17408
	ds_read_b128 v[174:177], v172 offset:19456
	ds_read_b128 v[182:185], v172 offset:21504
	ds_read_b128 v[190:193], v172 offset:23552
	global_load_lds_dwordx4 v[210:211], off
	s_mov_b32 m0, s26
	v_lshl_add_u64 v[210:211], s[18:19], 0, v[158:159]
	global_load_lds_dwordx4 v[210:211], off
	s_barrier
; #define PG8_STAGE(bufoff, gbase, voff) do { _Pragma("unroll") for (int _i = 0; _i < 2; ++_i) \
;         __builtin_amdgcn_global_load_lds((const unsigned*)((const char*)(gbase) + (voff)[_i]), (LAS unsigned*)(lds + (bufoff) + ldsw + _i * 8192), 16, 0, 0); } while (0)
; #define PG8_LDA(dst, b, h) do { _Pragma("unroll") for (int m = 0; m < 4; ++m) _Pragma("unroll") for (int k = 0; k < 2; ++k) dst[m][k] = *(const LAS bf16x8*)(lds + PG8_SA(b, h) + aoff + m * 2048 + k * 1024); } while (0)
; #define PG8_LDB(dst, b, h) do { _Pragma("unroll") for (int n = 0; n < 2; ++n) _Pragma("unroll") for (int k = 0; k < 2; ++k) dst[n][k] = *(const LAS bf16x8*)(lds + PG8_SB(b, h) + boff + n * 2048 + k * 1024); } while (0)
; #define PG8_MMA(ai, bj, At, Bt) do { __builtin_amdgcn_s_setprio(1); _Pragma("unroll") for (int m = 0; m < 4; ++m) _Pragma("unroll") for (int n = 0; n < 2; ++n) _Pragma("unroll") for (int k = 0; k < 2; ++k) \
;         acc[ai][bj][m][n] = __builtin_amdgcn_mfma_f32_16x16x32_bf16(Bt[n][k], At[m][k], acc[ai][bj][m][n], 0, 0, 0); __builtin_amdgcn_s_setprio(0); } while (0)
; #define PG8_WAIT_V(n) asm volatile("s_waitcnt vmcnt(" #n ")" ::: "memory")
; #define PG8_WAIT_L(n) asm volatile("s_waitcnt lgkmcnt(" #n ")" ::: "memory")
; #define PG8_BAR __builtin_amdgcn_s_barrier()
; #define PG8_SCHED __builtin_amdgcn_sched_barrier(0)
; template <class Epi>
; __device__ __forceinline__ void gemm_phase(LAS unsigned char* lds, const Gemm g, const StaticOrder& S, const Epi& E) {
;     ...
;             PG8_BAR; PG8_WAIT_L(0); PG8_MMA(1, 0, At, B0); PG8_BAR; PG8_SCHED;
;             PG8_STAGE(PG8_SB(0, 1), b2 + hstepB, voffB);
;             PG8_WAIT_V(6); PG8_BAR; PG8_MMA(1, 1, At, B1); PG8_BAR;
;             PG8_LDB(B0, 1, 0); PG8_SCHED; PG8_LDA(At, 1, 0); PG8_STAGE(PG8_SA(0, 1), a2 + hstepA, voffA);
;             PG8_WAIT_L(8); PG8_BAR; PG8_WAIT_L(0); PG8_MMA(0, 0, At, B0); PG8_BAR; PG8_SCHED;
;             PG8_LDB(B1, 1, 1); PG8_STAGE(PG8_SB(1, 0), b3, voffB);
	s_waitcnt lgkmcnt(7)
	v_mfma_f32_16x16x32_bf16 v[60:63], v[128:131], v[144:147], 0
	s_setprio 1
	v_mfma_f32_16x16x32_bf16 v[56:59], v[136:139], v[144:147], 0
	s_waitcnt lgkmcnt(6)
	v_mfma_f32_16x16x32_bf16 v[44:47], v[128:131], v[166:169], 0
	v_mfma_f32_16x16x32_bf16 v[40:43], v[136:139], v[166:169], 0
	s_waitcnt lgkmcnt(5)
	v_mfma_f32_16x16x32_bf16 v[28:31], v[128:131], v[178:181], 0
	v_mfma_f32_16x16x32_bf16 v[24:27], v[136:139], v[178:181], 0
	s_waitcnt lgkmcnt(4)
	v_mfma_f32_16x16x32_bf16 v[12:15], v[128:131], v[186:189], 0
	v_mfma_f32_16x16x32_bf16 v[8:11], v[136:139], v[186:189], 0
	s_waitcnt lgkmcnt(3)
	v_mfma_f32_16x16x32_bf16 v[60:63], v[132:135], v[148:151], v[60:63]
	v_mfma_f32_16x16x32_bf16 v[56:59], v[140:143], v[148:151], v[56:59]
	s_waitcnt lgkmcnt(2)
	v_mfma_f32_16x16x32_bf16 v[44:47], v[132:135], v[174:177], v[44:47]
	v_mfma_f32_16x16x32_bf16 v[40:43], v[140:143], v[174:177], v[40:43]
	s_waitcnt lgkmcnt(1)
	v_mfma_f32_16x16x32_bf16 v[28:31], v[132:135], v[182:185], v[28:31]
	v_mfma_f32_16x16x32_bf16 v[24:27], v[140:143], v[182:185], v[24:27]
	s_waitcnt lgkmcnt(0)
	v_mfma_f32_16x16x32_bf16 v[12:15], v[132:135], v[190:193], v[12:15]
	s_setprio 0
	v_mfma_f32_16x16x32_bf16 v[8:11], v[140:143], v[190:193], v[8:11]
	s_barrier
	s_add_u32 s40, s14, 0x80000
	s_addc_u32 s41, s15, 0
	s_add_i32 s39, s42, s23
	s_mov_b32 m0, s39
	v_lshl_add_u64 v[128:129], s[40:41], 0, v[156:157]
	global_load_lds_dwordx4 v[128:129], off
	s_add_i32 m0, s39, 0x2000
	v_lshl_add_u64 v[128:129], s[40:41], 0, v[158:159]
	global_load_lds_dwordx4 v[128:129], off
	s_waitcnt vmcnt(6)
	s_barrier
	v_mfma_f32_16x16x32_bf16 v[52:55], v[194:197], v[144:147], 0
	s_setprio 1
	v_mfma_f32_16x16x32_bf16 v[48:51], v[202:205], v[144:147], 0
	s_add_i32 s39, 0, 0x18000
	v_add_u32_e32 v140, s39, v170
	v_mfma_f32_16x16x32_bf16 v[36:39], v[194:197], v[166:169], 0
	v_mfma_f32_16x16x32_bf16 v[32:35], v[202:205], v[166:169], 0
	v_mfma_f32_16x16x32_bf16 v[20:23], v[194:197], v[178:181], 0
	v_mfma_f32_16x16x32_bf16 v[16:19], v[202:205], v[178:181], 0
	v_mfma_f32_16x16x32_bf16 v[4:7], v[194:197], v[186:189], 0
	v_mfma_f32_16x16x32_bf16 v[0:3], v[202:205], v[186:189], 0
	v_mfma_f32_16x16x32_bf16 v[52:55], v[198:201], v[148:151], v[52:55]
	v_mfma_f32_16x16x32_bf16 v[48:51], v[206:209], v[148:151], v[48:51]
	v_mfma_f32_16x16x32_bf16 v[36:39], v[198:201], v[174:177], v[36:39]
	v_mfma_f32_16x16x32_bf16 v[32:35], v[206:209], v[174:177], v[32:35]
	v_mfma_f32_16x16x32_bf16 v[20:23], v[198:201], v[182:185], v[20:23]
	v_mfma_f32_16x16x32_bf16 v[16:19], v[206:209], v[182:185], v[16:19]
	v_mfma_f32_16x16x32_bf16 v[4:7], v[198:201], v[190:193], v[4:7]
	s_setprio 0
	v_mfma_f32_16x16x32_bf16 v[0:3], v[206:209], v[190:193], v[0:3]
	s_barrier
	ds_read_b128 v[128:131], v140
	ds_read_b128 v[136:139], v140 offset:2048
	ds_read_b128 v[132:135], v140 offset:1024
	ds_read_b128 v[140:143], v140 offset:3072
	s_add_u32 s18, s18, 0x80000
	s_addc_u32 s19, s19, 0
	s_mov_b32 m0, s27
	v_lshl_add_u64 v[194:195], s[18:19], 0, v[156:157]
	ds_read_b128 v[144:147], v172 offset:32768
	ds_read_b128 v[166:169], v172 offset:34816
	ds_read_b128 v[178:181], v172 offset:36864
	ds_read_b128 v[186:189], v172 offset:38912
	ds_read_b128 v[148:151], v172 offset:33792
	ds_read_b128 v[174:177], v172 offset:35840
	ds_read_b128 v[182:185], v172 offset:37888
	ds_read_b128 v[190:193], v172 offset:39936
	global_load_lds_dwordx4 v[194:195], off
	s_mov_b32 m0, s28
	v_lshl_add_u64 v[194:195], s[18:19], 0, v[158:159]
	global_load_lds_dwordx4 v[194:195], off
	s_waitcnt lgkmcnt(8)
	s_barrier
	s_waitcnt lgkmcnt(7)
	v_mfma_f32_16x16x32_bf16 v[124:127], v[128:131], v[144:147], v[124:127]
	s_setprio 1
	v_mfma_f32_16x16x32_bf16 v[120:123], v[136:139], v[144:147], v[120:123]
	s_waitcnt lgkmcnt(6)
	v_mfma_f32_16x16x32_bf16 v[108:111], v[128:131], v[166:169], v[108:111]
	v_mfma_f32_16x16x32_bf16 v[104:107], v[136:139], v[166:169], v[104:107]
	s_waitcnt lgkmcnt(5)
	v_mfma_f32_16x16x32_bf16 v[92:95], v[128:131], v[178:181], v[92:95]
	v_mfma_f32_16x16x32_bf16 v[88:91], v[136:139], v[178:181], v[88:91]
	s_waitcnt lgkmcnt(4)
	v_mfma_f32_16x16x32_bf16 v[76:79], v[128:131], v[186:189], v[76:79]
	v_mfma_f32_16x16x32_bf16 v[72:75], v[136:139], v[186:189], v[72:75]
	s_waitcnt lgkmcnt(3)
	v_mfma_f32_16x16x32_bf16 v[124:127], v[132:135], v[148:151], v[124:127]
	v_mfma_f32_16x16x32_bf16 v[120:123], v[140:143], v[148:151], v[120:123]
	s_waitcnt lgkmcnt(2)
	v_mfma_f32_16x16x32_bf16 v[108:111], v[132:135], v[174:177], v[108:111]
	v_mfma_f32_16x16x32_bf16 v[104:107], v[140:143], v[174:177], v[104:107]
	s_waitcnt lgkmcnt(1)
	v_mfma_f32_16x16x32_bf16 v[92:95], v[132:135], v[182:185], v[92:95]
	v_mfma_f32_16x16x32_bf16 v[88:91], v[140:143], v[182:185], v[88:91]
	s_waitcnt lgkmcnt(0)
	v_mfma_f32_16x16x32_bf16 v[76:79], v[132:135], v[190:193], v[76:79]
	s_setprio 0
	v_mfma_f32_16x16x32_bf16 v[72:75], v[140:143], v[190:193], v[72:75]
	s_barrier
	s_add_i32 s40, 0, 0x1c000
	s_add_u32 s18, s14, 0x4000
	s_addc_u32 s19, s15, 0
	s_add_i32 s39, s39, s23
	v_add_u32_e32 v152, s40, v170
	v_lshl_add_u64 v[210:211], s[18:19], 0, v[156:157]
	s_mov_b32 m0, s39
	ds_read_b128 v[194:197], v152
	ds_read_b128 v[202:205], v152 offset:2048
	ds_read_b128 v[198:201], v152 offset:1024
	ds_read_b128 v[206:209], v152 offset:3072
	global_load_lds_dwordx4 v[210:211], off
	s_add_i32 m0, s39, 0x2000
	v_lshl_add_u64 v[210:211], s[18:19], 0, v[158:159]
	global_load_lds_dwordx4 v[210:211], off
	s_barrier
; #define PG8_STAGE(bufoff, gbase, voff) do { _Pragma("unroll") for (int _i = 0; _i < 2; ++_i) \
;         __builtin_amdgcn_global_load_lds((const unsigned*)((const char*)(gbase) + (voff)[_i]), (LAS unsigned*)(lds + (bufoff) + ldsw + _i * 8192), 16, 0, 0); } while (0)
; #define PG8_LDA(dst, b, h) do { _Pragma("unroll") for (int m = 0; m < 4; ++m) _Pragma("unroll") for (int k = 0; k < 2; ++k) dst[m][k] = *(const LAS bf16x8*)(lds + PG8_SA(b, h) + aoff + m * 2048 + k * 1024); } while (0)
; #define PG8_MMA(ai, bj, At, Bt) do { __builtin_amdgcn_s_setprio(1); _Pragma("unroll") for (int m = 0; m < 4; ++m) _Pragma("unroll") for (int n = 0; n < 2; ++n) _Pragma("unroll") for (int k = 0; k < 2; ++k) \
;         acc[ai][bj][m][n] = __builtin_amdgcn_mfma_f32_16x16x32_bf16(Bt[n][k], At[m][k], acc[ai][bj][m][n], 0, 0, 0); __builtin_amdgcn_s_setprio(0); } while (0)
; #define PG8_WAIT_V(n) asm volatile("s_waitcnt vmcnt(" #n ")" ::: "memory")
; #define PG8_WAIT_L(n) asm volatile("s_waitcnt lgkmcnt(" #n ")" ::: "memory")
; #define PG8_BAR __builtin_amdgcn_s_barrier()
; #define PG8_SCHED __builtin_amdgcn_sched_barrier(0)
; template <class Epi>
; __device__ __forceinline__ void gemm_phase(LAS unsigned char* lds, const Gemm g, const StaticOrder& S, const Epi& E) {
;     ...
;             PG8_BAR; PG8_WAIT_L(0); PG8_MMA(0, 1, At, B1); PG8_BAR;
;             PG8_LDA(At, 1, 1); PG8_STAGE(PG8_SA(1, 0), a3, voffA);
;             PG8_BAR; PG8_WAIT_L(0); PG8_MMA(1, 0, At, B0); PG8_BAR; PG8_SCHED;
;             PG8_STAGE(PG8_SB(1, 1), b3 + hstepB, voffB);
;             PG8_WAIT_V(6); PG8_BAR; PG8_MMA(1, 1, At, B1); PG8_BAR;
;         }
	s_waitcnt lgkmcnt(3)
	v_mfma_f32_16x16x32_bf16 v[116:119], v[194:197], v[144:147], v[116:119]
	s_setprio 1
	s_waitcnt lgkmcnt(2)
	v_mfma_f32_16x16x32_bf16 v[112:115], v[202:205], v[144:147], v[112:115]
	s_mov_b32 m0, s29
	v_lshl_add_u64 v[210:211], s[16:17], 0, v[156:157]
	v_mfma_f32_16x16x32_bf16 v[100:103], v[194:197], v[166:169], v[100:103]
	v_mfma_f32_16x16x32_bf16 v[96:99], v[202:205], v[166:169], v[96:99]
	v_mfma_f32_16x16x32_bf16 v[84:87], v[194:197], v[178:181], v[84:87]
	v_mfma_f32_16x16x32_bf16 v[80:83], v[202:205], v[178:181], v[80:83]
	v_mfma_f32_16x16x32_bf16 v[68:71], v[194:197], v[186:189], v[68:71]
	v_mfma_f32_16x16x32_bf16 v[64:67], v[202:205], v[186:189], v[64:67]
	s_waitcnt lgkmcnt(1)
	v_mfma_f32_16x16x32_bf16 v[116:119], v[198:201], v[148:151], v[116:119]
	s_waitcnt lgkmcnt(0)
	v_mfma_f32_16x16x32_bf16 v[112:115], v[206:209], v[148:151], v[112:115]
	v_mfma_f32_16x16x32_bf16 v[100:103], v[198:201], v[174:177], v[100:103]
	v_mfma_f32_16x16x32_bf16 v[96:99], v[206:209], v[174:177], v[96:99]
	v_mfma_f32_16x16x32_bf16 v[84:87], v[198:201], v[182:185], v[84:87]
	v_mfma_f32_16x16x32_bf16 v[80:83], v[206:209], v[182:185], v[80:83]
	v_mfma_f32_16x16x32_bf16 v[68:71], v[198:201], v[190:193], v[68:71]
	s_setprio 0
	v_mfma_f32_16x16x32_bf16 v[64:67], v[206:209], v[190:193], v[64:67]
	s_barrier
	ds_read_b128 v[144:147], v172 offset:49152
	ds_read_b128 v[166:169], v172 offset:51200
	ds_read_b128 v[178:181], v172 offset:53248
	ds_read_b128 v[186:189], v172 offset:55296
	ds_read_b128 v[148:151], v172 offset:50176
	ds_read_b128 v[174:177], v172 offset:52224
	ds_read_b128 v[182:185], v172 offset:54272
	ds_read_b128 v[190:193], v172 offset:56320
	global_load_lds_dwordx4 v[210:211], off
	s_mov_b32 m0, s30
	v_lshl_add_u64 v[210:211], s[16:17], 0, v[158:159]
	global_load_lds_dwordx4 v[210:211], off
	s_barrier
	s_waitcnt lgkmcnt(7)
	v_mfma_f32_16x16x32_bf16 v[60:63], v[128:131], v[144:147], v[60:63]
	s_setprio 1
	v_mfma_f32_16x16x32_bf16 v[56:59], v[136:139], v[144:147], v[56:59]
	s_waitcnt lgkmcnt(6)
	v_mfma_f32_16x16x32_bf16 v[44:47], v[128:131], v[166:169], v[44:47]
	v_mfma_f32_16x16x32_bf16 v[40:43], v[136:139], v[166:169], v[40:43]
	s_waitcnt lgkmcnt(5)
	v_mfma_f32_16x16x32_bf16 v[28:31], v[128:131], v[178:181], v[28:31]
	v_mfma_f32_16x16x32_bf16 v[24:27], v[136:139], v[178:181], v[24:27]
	s_waitcnt lgkmcnt(4)
	v_mfma_f32_16x16x32_bf16 v[12:15], v[128:131], v[186:189], v[12:15]
	v_mfma_f32_16x16x32_bf16 v[8:11], v[136:139], v[186:189], v[8:11]
	s_waitcnt lgkmcnt(3)
	v_mfma_f32_16x16x32_bf16 v[60:63], v[132:135], v[148:151], v[60:63]
	v_mfma_f32_16x16x32_bf16 v[56:59], v[140:143], v[148:151], v[56:59]
	s_waitcnt lgkmcnt(2)
	v_mfma_f32_16x16x32_bf16 v[44:47], v[132:135], v[174:177], v[44:47]
	v_mfma_f32_16x16x32_bf16 v[40:43], v[140:143], v[174:177], v[40:43]
	s_waitcnt lgkmcnt(1)
	v_mfma_f32_16x16x32_bf16 v[28:31], v[132:135], v[182:185], v[28:31]
	v_mfma_f32_16x16x32_bf16 v[24:27], v[140:143], v[182:185], v[24:27]
	s_waitcnt lgkmcnt(0)
	v_mfma_f32_16x16x32_bf16 v[12:15], v[132:135], v[190:193], v[12:15]
	s_setprio 0
	v_mfma_f32_16x16x32_bf16 v[8:11], v[140:143], v[190:193], v[8:11]
	s_barrier
	s_add_u32 s14, s14, 0x84000
	s_addc_u32 s15, s15, 0
	s_add_i32 s16, s40, s23
	s_mov_b32 m0, s16
	v_lshl_add_u64 v[128:129], s[14:15], 0, v[156:157]
	global_load_lds_dwordx4 v[128:129], off
	s_add_i32 m0, s16, 0x2000
	v_lshl_add_u64 v[128:129], s[14:15], 0, v[158:159]
	global_load_lds_dwordx4 v[128:129], off
	s_waitcnt vmcnt(6)
	s_barrier
	v_mfma_f32_16x16x32_bf16 v[52:55], v[194:197], v[144:147], v[52:55]
	s_setprio 1
	v_mfma_f32_16x16x32_bf16 v[48:51], v[202:205], v[144:147], v[48:51]
	s_add_i32 s38, s38, 2
	s_add_u32 s12, s12, 0x8000
	s_addc_u32 s13, s13, 0
	s_add_u32 s36, s36, 0x8000
	s_addc_u32 s37, s37, 0
	v_mfma_f32_16x16x32_bf16 v[36:39], v[194:197], v[166:169], v[36:39]
	v_mfma_f32_16x16x32_bf16 v[32:35], v[202:205], v[166:169], v[32:35]
	v_mfma_f32_16x16x32_bf16 v[20:23], v[194:197], v[178:181], v[20:23]
	v_mfma_f32_16x16x32_bf16 v[16:19], v[202:205], v[178:181], v[16:19]
	v_mfma_f32_16x16x32_bf16 v[4:7], v[194:197], v[186:189], v[4:7]
	v_mfma_f32_16x16x32_bf16 v[0:3], v[202:205], v[186:189], v[0:3]
	v_mfma_f32_16x16x32_bf16 v[52:55], v[198:201], v[148:151], v[52:55]
	v_mfma_f32_16x16x32_bf16 v[48:51], v[206:209], v[148:151], v[48:51]
	v_mfma_f32_16x16x32_bf16 v[36:39], v[198:201], v[174:177], v[36:39]
	v_mfma_f32_16x16x32_bf16 v[32:35], v[206:209], v[174:177], v[32:35]
	v_mfma_f32_16x16x32_bf16 v[20:23], v[198:201], v[182:185], v[20:23]
	v_mfma_f32_16x16x32_bf16 v[16:19], v[206:209], v[182:185], v[16:19]
	v_mfma_f32_16x16x32_bf16 v[4:7], v[198:201], v[190:193], v[4:7]
	s_cmp_gt_u32 s38, 29
	s_setprio 0
	v_mfma_f32_16x16x32_bf16 v[0:3], v[206:209], v[190:193], v[0:3]
	s_barrier
	s_cbranch_scc0 .LBB0_247
	s_branch .Lpeel_done_247
; #define PG8_STAGE(bufoff, gbase, voff) do { _Pragma("unroll") for (int _i = 0; _i < 2; ++_i) \
;         __builtin_amdgcn_global_load_lds((const unsigned*)((const char*)(gbase) + (voff)[_i]), (LAS unsigned*)(lds + (bufoff) + ldsw + _i * 8192), 16, 0, 0); } while (0)
; #define PG8_LDA(dst, b, h) do { _Pragma("unroll") for (int m = 0; m < 4; ++m) _Pragma("unroll") for (int k = 0; k < 2; ++k) dst[m][k] = *(const LAS bf16x8*)(lds + PG8_SA(b, h) + aoff + m * 2048 + k * 1024); } while (0)
; #define PG8_LDB(dst, b, h) do { _Pragma("unroll") for (int n = 0; n < 2; ++n) _Pragma("unroll") for (int k = 0; k < 2; ++k) dst[n][k] = *(const LAS bf16x8*)(lds + PG8_SB(b, h) + boff + n * 2048 + k * 1024); } while (0)
; #define PG8_MMA(ai, bj, At, Bt) do { __builtin_amdgcn_s_setprio(1); _Pragma("unroll") for (int m = 0; m < 4; ++m) _Pragma("unroll") for (int n = 0; n < 2; ++n) _Pragma("unroll") for (int k = 0; k < 2; ++k) \
;         acc[ai][bj][m][n] = __builtin_amdgcn_mfma_f32_16x16x32_bf16(Bt[n][k], At[m][k], acc[ai][bj][m][n], 0, 0, 0); __builtin_amdgcn_s_setprio(0); } while (0)
; #define PG8_WAIT_L(n) asm volatile("s_waitcnt lgkmcnt(" #n ")" ::: "memory")
; #define PG8_BAR __builtin_amdgcn_s_barrier()
; #define PG8_SCHED __builtin_amdgcn_sched_barrier(0)
; template <class Epi>
; __device__ __forceinline__ void gemm_phase(LAS unsigned char* lds, const Gemm g, const StaticOrder& S, const Epi& E) {
;     ...
;             const bool last = (t == nt - 2);
;             const char* a1 = cA + (size_t)(t + 1) * kstep;
;             const char* a2 = last ? nA : cA + (size_t)(t + 2) * kstep; const char* b2 = last ? nB : cB + (size_t)(t + 2) * kstep;
;             const char* a3 = a2 + kstep; const char* b3 = b2 + kstep;
;             PG8_LDB(B0, 0, 0); PG8_SCHED; PG8_LDA(At, 0, 0); PG8_STAGE(PG8_SA(1, 1), a1 + hstepA, voffA);
;             PG8_WAIT_L(8); PG8_BAR; PG8_WAIT_L(0); PG8_MMA(0, 0, At, B0); PG8_BAR; PG8_SCHED;
;             PG8_LDB(B1, 0, 1); PG8_STAGE(PG8_SB(0, 0), b2, voffB);
;             PG8_BAR; PG8_WAIT_L(0); PG8_MMA(0, 1, At, B1); PG8_BAR;
;             PG8_LDA(At, 0, 1); PG8_STAGE(PG8_SA(0, 0), a2, voffA);
;             PG8_BAR; PG8_WAIT_L(0); PG8_MMA(1, 0, At, B0); PG8_BAR; PG8_SCHED;
.LBB0_247:
	s_add_u32 s14, s12, 0xfff84000
	s_addc_u32 s15, s13, -1
	s_cmp_eq_u32 s38, 28
	s_cselect_b32 s18, s11, s14
	s_cselect_b32 s19, s5, s15
	s_cselect_b32 s14, s35, s36
	s_cselect_b32 s15, s3, s37
	s_add_u32 s16, s18, 0x4000
	s_addc_u32 s17, s19, 0
	s_add_i32 s39, 0, 0x10000
	v_add_u32_e32 v140, s39, v170
	ds_read_b128 v[128:131], v140
	ds_read_b128 v[136:139], v140 offset:2048
	ds_read_b128 v[132:135], v140 offset:1024
	ds_read_b128 v[140:143], v140 offset:3072
	v_lshl_add_u64 v[194:195], s[12:13], 0, v[156:157]
	s_add_i32 m0, s25, 0xc000
	ds_read_b128 v[144:147], v172
	ds_read_b128 v[166:169], v172 offset:2048
	ds_read_b128 v[178:181], v172 offset:4096
	ds_read_b128 v[186:189], v172 offset:6144
	ds_read_b128 v[148:151], v172 offset:1024
	ds_read_b128 v[174:177], v172 offset:3072
	ds_read_b128 v[182:185], v172 offset:5120
	ds_read_b128 v[190:193], v172 offset:7168
	global_load_lds_dwordx4 v[194:195], off
	s_add_i32 m0, s25, 0xe000
	v_lshl_add_u64 v[194:195], s[12:13], 0, v[158:159]
	global_load_lds_dwordx4 v[194:195], off
	s_waitcnt lgkmcnt(8)
	s_barrier
	s_waitcnt lgkmcnt(7)
	v_mfma_f32_16x16x32_bf16 v[124:127], v[128:131], v[144:147], v[124:127]
	s_setprio 1
	v_mfma_f32_16x16x32_bf16 v[120:123], v[136:139], v[144:147], v[120:123]
	s_waitcnt lgkmcnt(6)
	v_mfma_f32_16x16x32_bf16 v[108:111], v[128:131], v[166:169], v[108:111]
	v_mfma_f32_16x16x32_bf16 v[104:107], v[136:139], v[166:169], v[104:107]
	s_waitcnt lgkmcnt(5)
	v_mfma_f32_16x16x32_bf16 v[92:95], v[128:131], v[178:181], v[92:95]
	v_mfma_f32_16x16x32_bf16 v[88:91], v[136:139], v[178:181], v[88:91]
	s_waitcnt lgkmcnt(4)
	v_mfma_f32_16x16x32_bf16 v[76:79], v[128:131], v[186:189], v[76:79]
	v_mfma_f32_16x16x32_bf16 v[72:75], v[136:139], v[186:189], v[72:75]
	s_waitcnt lgkmcnt(3)
	v_mfma_f32_16x16x32_bf16 v[124:127], v[132:135], v[148:151], v[124:127]
	v_mfma_f32_16x16x32_bf16 v[120:123], v[140:143], v[148:151], v[120:123]
	s_waitcnt lgkmcnt(2)
	v_mfma_f32_16x16x32_bf16 v[108:111], v[132:135], v[174:177], v[108:111]
	v_mfma_f32_16x16x32_bf16 v[104:107], v[140:143], v[174:177], v[104:107]
	s_waitcnt lgkmcnt(1)
	v_mfma_f32_16x16x32_bf16 v[92:95], v[132:135], v[182:185], v[92:95]
	v_mfma_f32_16x16x32_bf16 v[88:91], v[140:143], v[182:185], v[88:91]
	s_waitcnt lgkmcnt(0)
	v_mfma_f32_16x16x32_bf16 v[76:79], v[132:135], v[190:193], v[76:79]
	s_setprio 0
	v_mfma_f32_16x16x32_bf16 v[72:75], v[140:143], v[190:193], v[72:75]
	s_barrier
	s_add_i32 s42, 0, 0x14000
	s_add_i32 s39, s39, s23
	v_add_u32_e32 v152, s42, v170
	v_lshl_add_u64 v[210:211], s[14:15], 0, v[156:157]
	s_mov_b32 m0, s39
	ds_read_b128 v[194:197], v152
	ds_read_b128 v[202:205], v152 offset:2048
	ds_read_b128 v[198:201], v152 offset:1024
	ds_read_b128 v[206:209], v152 offset:3072
	global_load_lds_dwordx4 v[210:211], off
	s_add_i32 m0, s39, 0x2000
	v_lshl_add_u64 v[210:211], s[14:15], 0, v[158:159]
	global_load_lds_dwordx4 v[210:211], off
	s_barrier
	s_waitcnt lgkmcnt(3)
	v_mfma_f32_16x16x32_bf16 v[116:119], v[194:197], v[144:147], v[116:119]
	s_setprio 1
	s_waitcnt lgkmcnt(2)
	v_mfma_f32_16x16x32_bf16 v[112:115], v[202:205], v[144:147], v[112:115]
	s_mov_b32 m0, s25
	v_lshl_add_u64 v[210:211], s[18:19], 0, v[156:157]
	v_mfma_f32_16x16x32_bf16 v[100:103], v[194:197], v[166:169], v[100:103]
	v_mfma_f32_16x16x32_bf16 v[96:99], v[202:205], v[166:169], v[96:99]
	v_mfma_f32_16x16x32_bf16 v[84:87], v[194:197], v[178:181], v[84:87]
	v_mfma_f32_16x16x32_bf16 v[80:83], v[202:205], v[178:181], v[80:83]
	v_mfma_f32_16x16x32_bf16 v[68:71], v[194:197], v[186:189], v[68:71]
	v_mfma_f32_16x16x32_bf16 v[64:67], v[202:205], v[186:189], v[64:67]
	s_waitcnt lgkmcnt(1)
	v_mfma_f32_16x16x32_bf16 v[116:119], v[198:201], v[148:151], v[116:119]
	s_waitcnt lgkmcnt(0)
	v_mfma_f32_16x16x32_bf16 v[112:115], v[206:209], v[148:151], v[112:115]
	v_mfma_f32_16x16x32_bf16 v[100:103], v[198:201], v[174:177], v[100:103]
	v_mfma_f32_16x16x32_bf16 v[96:99], v[206:209], v[174:177], v[96:99]
	v_mfma_f32_16x16x32_bf16 v[84:87], v[198:201], v[182:185], v[84:87]
	v_mfma_f32_16x16x32_bf16 v[80:83], v[206:209], v[182:185], v[80:83]
	v_mfma_f32_16x16x32_bf16 v[68:71], v[198:201], v[190:193], v[68:71]
	s_setprio 0
	v_mfma_f32_16x16x32_bf16 v[64:67], v[206:209], v[190:193], v[64:67]
	s_barrier
	ds_read_b128 v[144:147], v172 offset:16384
	ds_read_b128 v[166:169], v172 offset:18432
	ds_read_b128 v[178:181], v172 offset:20480
	ds_read_b128 v[186:189], v172 offset:22528
	ds_read_b128 v[148:151], v172 offset:17408
	ds_read_b128 v[174:177], v172 offset:19456
	ds_read_b128 v[182:185], v172 offset:21504
	ds_read_b128 v[190:193], v172 offset:23552
	global_load_lds_dwordx4 v[210:211], off
	s_mov_b32 m0, s26
	v_lshl_add_u64 v[210:211], s[18:19], 0, v[158:159]
	global_load_lds_dwordx4 v[210:211], off
	s_barrier
	s_waitcnt lgkmcnt(7)
	v_mfma_f32_16x16x32_bf16 v[60:63], v[128:131], v[144:147], v[60:63]
	s_setprio 1
	v_mfma_f32_16x16x32_bf16 v[56:59], v[136:139], v[144:147], v[56:59]
	s_waitcnt lgkmcnt(6)
	v_mfma_f32_16x16x32_bf16 v[44:47], v[128:131], v[166:169], v[44:47]
	v_mfma_f32_16x16x32_bf16 v[40:43], v[136:139], v[166:169], v[40:43]
	s_waitcnt lgkmcnt(5)
	v_mfma_f32_16x16x32_bf16 v[28:31], v[128:131], v[178:181], v[28:31]
	v_mfma_f32_16x16x32_bf16 v[24:27], v[136:139], v[178:181], v[24:27]
	s_waitcnt lgkmcnt(4)
	v_mfma_f32_16x16x32_bf16 v[12:15], v[128:131], v[186:189], v[12:15]
	v_mfma_f32_16x16x32_bf16 v[8:11], v[136:139], v[186:189], v[8:11]
	s_waitcnt lgkmcnt(3)
	v_mfma_f32_16x16x32_bf16 v[60:63], v[132:135], v[148:151], v[60:63]
	v_mfma_f32_16x16x32_bf16 v[56:59], v[140:143], v[148:151], v[56:59]
	s_waitcnt lgkmcnt(2)
	v_mfma_f32_16x16x32_bf16 v[44:47], v[132:135], v[174:177], v[44:47]
	v_mfma_f32_16x16x32_bf16 v[40:43], v[140:143], v[174:177], v[40:43]
	s_waitcnt lgkmcnt(1)
	v_mfma_f32_16x16x32_bf16 v[28:31], v[132:135], v[182:185], v[28:31]
	v_mfma_f32_16x16x32_bf16 v[24:27], v[140:143], v[182:185], v[24:27]
	s_waitcnt lgkmcnt(0)
	v_mfma_f32_16x16x32_bf16 v[12:15], v[132:135], v[190:193], v[12:15]
	s_setprio 0
	v_mfma_f32_16x16x32_bf16 v[8:11], v[140:143], v[190:193], v[8:11]
	s_barrier
; #define PG8_STAGE(bufoff, gbase, voff) do { _Pragma("unroll") for (int _i = 0; _i < 2; ++_i) \
;         __builtin_amdgcn_global_load_lds((const unsigned*)((const char*)(gbase) + (voff)[_i]), (LAS unsigned*)(lds + (bufoff) + ldsw + _i * 8192), 16, 0, 0); } while (0)
; #define PG8_LDA(dst, b, h) do { _Pragma("unroll") for (int m = 0; m < 4; ++m) _Pragma("unroll") for (int k = 0; k < 2; ++k) dst[m][k] = *(const LAS bf16x8*)(lds + PG8_SA(b, h) + aoff + m * 2048 + k * 1024); } while (0)
; #define PG8_LDB(dst, b, h) do { _Pragma("unroll") for (int n = 0; n < 2; ++n) _Pragma("unroll") for (int k = 0; k < 2; ++k) dst[n][k] = *(const LAS bf16x8*)(lds + PG8_SB(b, h) + boff + n * 2048 + k * 1024); } while (0)
; #define PG8_MMA(ai, bj, At, Bt) do { __builtin_amdgcn_s_setprio(1); _Pragma("unroll") for (int m = 0; m < 4; ++m) _Pragma("unroll") for (int n = 0; n < 2; ++n) _Pragma("unroll") for (int k = 0; k < 2; ++k) \
;         acc[ai][bj][m][n] = __builtin_amdgcn_mfma_f32_16x16x32_bf16(Bt[n][k], At[m][k], acc[ai][bj][m][n], 0, 0, 0); __builtin_amdgcn_s_setprio(0); } while (0)
; #define PG8_WAIT_V(n) asm volatile("s_waitcnt vmcnt(" #n ")" ::: "memory")
; #define PG8_WAIT_L(n) asm volatile("s_waitcnt lgkmcnt(" #n ")" ::: "memory")
; #define PG8_BAR __builtin_amdgcn_s_barrier()
; #define PG8_SCHED __builtin_amdgcn_sched_barrier(0)
; template <class Epi>
; __device__ __forceinline__ void gemm_phase(LAS unsigned char* lds, const Gemm g, const StaticOrder& S, const Epi& E) {
;     ...
;             PG8_STAGE(PG8_SB(0, 1), b2 + hstepB, voffB);
;             PG8_WAIT_V(6); PG8_BAR; PG8_MMA(1, 1, At, B1); PG8_BAR;
;             PG8_LDB(B0, 1, 0); PG8_SCHED; PG8_LDA(At, 1, 0); PG8_STAGE(PG8_SA(0, 1), a2 + hstepA, voffA);
;             PG8_WAIT_L(8); PG8_BAR; PG8_WAIT_L(0); PG8_MMA(0, 0, At, B0); PG8_BAR; PG8_SCHED;
;             PG8_LDB(B1, 1, 1); PG8_STAGE(PG8_SB(1, 0), b3, voffB);
	s_add_u32 s40, s14, 0x80000
	s_addc_u32 s41, s15, 0
	s_add_i32 s39, s42, s23
	s_mov_b32 m0, s39
	v_lshl_add_u64 v[128:129], s[40:41], 0, v[156:157]
	global_load_lds_dwordx4 v[128:129], off
	s_add_i32 m0, s39, 0x2000
	v_lshl_add_u64 v[128:129], s[40:41], 0, v[158:159]
	global_load_lds_dwordx4 v[128:129], off
	s_waitcnt vmcnt(6)
	s_barrier
	v_mfma_f32_16x16x32_bf16 v[52:55], v[194:197], v[144:147], v[52:55]
	s_setprio 1
	v_mfma_f32_16x16x32_bf16 v[48:51], v[202:205], v[144:147], v[48:51]
	s_add_i32 s39, 0, 0x18000
	v_add_u32_e32 v140, s39, v170
	v_mfma_f32_16x16x32_bf16 v[36:39], v[194:197], v[166:169], v[36:39]
	v_mfma_f32_16x16x32_bf16 v[32:35], v[202:205], v[166:169], v[32:35]
	v_mfma_f32_16x16x32_bf16 v[20:23], v[194:197], v[178:181], v[20:23]
	v_mfma_f32_16x16x32_bf16 v[16:19], v[202:205], v[178:181], v[16:19]
	v_mfma_f32_16x16x32_bf16 v[4:7], v[194:197], v[186:189], v[4:7]
	v_mfma_f32_16x16x32_bf16 v[0:3], v[202:205], v[186:189], v[0:3]
	v_mfma_f32_16x16x32_bf16 v[52:55], v[198:201], v[148:151], v[52:55]
	v_mfma_f32_16x16x32_bf16 v[48:51], v[206:209], v[148:151], v[48:51]
	v_mfma_f32_16x16x32_bf16 v[36:39], v[198:201], v[174:177], v[36:39]
	v_mfma_f32_16x16x32_bf16 v[32:35], v[206:209], v[174:177], v[32:35]
	v_mfma_f32_16x16x32_bf16 v[20:23], v[198:201], v[182:185], v[20:23]
	v_mfma_f32_16x16x32_bf16 v[16:19], v[206:209], v[182:185], v[16:19]
	v_mfma_f32_16x16x32_bf16 v[4:7], v[198:201], v[190:193], v[4:7]
	s_setprio 0
	v_mfma_f32_16x16x32_bf16 v[0:3], v[206:209], v[190:193], v[0:3]
	s_barrier
	ds_read_b128 v[128:131], v140
	ds_read_b128 v[136:139], v140 offset:2048
	ds_read_b128 v[132:135], v140 offset:1024
	ds_read_b128 v[140:143], v140 offset:3072
	s_add_u32 s18, s18, 0x80000
	s_addc_u32 s19, s19, 0
	s_mov_b32 m0, s27
	v_lshl_add_u64 v[194:195], s[18:19], 0, v[156:157]
	ds_read_b128 v[144:147], v172 offset:32768
	ds_read_b128 v[166:169], v172 offset:34816
	ds_read_b128 v[178:181], v172 offset:36864
	ds_read_b128 v[186:189], v172 offset:38912
	ds_read_b128 v[148:151], v172 offset:33792
	ds_read_b128 v[174:177], v172 offset:35840
	ds_read_b128 v[182:185], v172 offset:37888
	ds_read_b128 v[190:193], v172 offset:39936
	global_load_lds_dwordx4 v[194:195], off
	s_mov_b32 m0, s28
	v_lshl_add_u64 v[194:195], s[18:19], 0, v[158:159]
	global_load_lds_dwordx4 v[194:195], off
	s_waitcnt lgkmcnt(8)
	s_barrier
	s_waitcnt lgkmcnt(7)
	v_mfma_f32_16x16x32_bf16 v[124:127], v[128:131], v[144:147], v[124:127]
	s_setprio 1
	v_mfma_f32_16x16x32_bf16 v[120:123], v[136:139], v[144:147], v[120:123]
	s_waitcnt lgkmcnt(6)
	v_mfma_f32_16x16x32_bf16 v[108:111], v[128:131], v[166:169], v[108:111]
	v_mfma_f32_16x16x32_bf16 v[104:107], v[136:139], v[166:169], v[104:107]
	s_waitcnt lgkmcnt(5)
	v_mfma_f32_16x16x32_bf16 v[92:95], v[128:131], v[178:181], v[92:95]
	v_mfma_f32_16x16x32_bf16 v[88:91], v[136:139], v[178:181], v[88:91]
	s_waitcnt lgkmcnt(4)
	v_mfma_f32_16x16x32_bf16 v[76:79], v[128:131], v[186:189], v[76:79]
	v_mfma_f32_16x16x32_bf16 v[72:75], v[136:139], v[186:189], v[72:75]
	s_waitcnt lgkmcnt(3)
	v_mfma_f32_16x16x32_bf16 v[124:127], v[132:135], v[148:151], v[124:127]
	v_mfma_f32_16x16x32_bf16 v[120:123], v[140:143], v[148:151], v[120:123]
	s_waitcnt lgkmcnt(2)
	v_mfma_f32_16x16x32_bf16 v[108:111], v[132:135], v[174:177], v[108:111]
	v_mfma_f32_16x16x32_bf16 v[104:107], v[140:143], v[174:177], v[104:107]
	s_waitcnt lgkmcnt(1)
	v_mfma_f32_16x16x32_bf16 v[92:95], v[132:135], v[182:185], v[92:95]
	v_mfma_f32_16x16x32_bf16 v[88:91], v[140:143], v[182:185], v[88:91]
	s_waitcnt lgkmcnt(0)
	v_mfma_f32_16x16x32_bf16 v[76:79], v[132:135], v[190:193], v[76:79]
	s_setprio 0
	v_mfma_f32_16x16x32_bf16 v[72:75], v[140:143], v[190:193], v[72:75]
	s_barrier
	s_add_i32 s40, 0, 0x1c000
	s_add_u32 s18, s14, 0x4000
	s_addc_u32 s19, s15, 0
	s_add_i32 s39, s39, s23
	v_add_u32_e32 v152, s40, v170
	v_lshl_add_u64 v[210:211], s[18:19], 0, v[156:157]
	s_mov_b32 m0, s39
	ds_read_b128 v[194:197], v152
	ds_read_b128 v[202:205], v152 offset:2048
	ds_read_b128 v[198:201], v152 offset:1024
	ds_read_b128 v[206:209], v152 offset:3072
	global_load_lds_dwordx4 v[210:211], off
	s_add_i32 m0, s39, 0x2000
	v_lshl_add_u64 v[210:211], s[18:19], 0, v[158:159]
	global_load_lds_dwordx4 v[210:211], off
	s_barrier
; #define PG8_STAGE(bufoff, gbase, voff) do { _Pragma("unroll") for (int _i = 0; _i < 2; ++_i) \
;         __builtin_amdgcn_global_load_lds((const unsigned*)((const char*)(gbase) + (voff)[_i]), (LAS unsigned*)(lds + (bufoff) + ldsw + _i * 8192), 16, 0, 0); } while (0)
; #define PG8_LDA(dst, b, h) do { _Pragma("unroll") for (int m = 0; m < 4; ++m) _Pragma("unroll") for (int k = 0; k < 2; ++k) dst[m][k] = *(const LAS bf16x8*)(lds + PG8_SA(b, h) + aoff + m * 2048 + k * 1024); } while (0)
; #define PG8_MMA(ai, bj, At, Bt) do { __builtin_amdgcn_s_setprio(1); _Pragma("unroll") for (int m = 0; m < 4; ++m) _Pragma("unroll") for (int n = 0; n < 2; ++n) _Pragma("unroll") for (int k = 0; k < 2; ++k) \
;         acc[ai][bj][m][n] = __builtin_amdgcn_mfma_f32_16x16x32_bf16(Bt[n][k], At[m][k], acc[ai][bj][m][n], 0, 0, 0); __builtin_amdgcn_s_setprio(0); } while (0)
; #define PG8_WAIT_V(n) asm volatile("s_waitcnt vmcnt(" #n ")" ::: "memory")
; #define PG8_WAIT_L(n) asm volatile("s_waitcnt lgkmcnt(" #n ")" ::: "memory")
; #define PG8_BAR __builtin_amdgcn_s_barrier()
; #define PG8_SCHED __builtin_amdgcn_sched_barrier(0)
; template <class Epi>
; __device__ __forceinline__ void gemm_phase(LAS unsigned char* lds, const Gemm g, const StaticOrder& S, const Epi& E) {
;     ...
;             PG8_BAR; PG8_WAIT_L(0); PG8_MMA(0, 1, At, B1); PG8_BAR;
;             PG8_LDA(At, 1, 1); PG8_STAGE(PG8_SA(1, 0), a3, voffA);
;             PG8_BAR; PG8_WAIT_L(0); PG8_MMA(1, 0, At, B0); PG8_BAR; PG8_SCHED;
;             PG8_STAGE(PG8_SB(1, 1), b3 + hstepB, voffB);
;             PG8_WAIT_V(6); PG8_BAR; PG8_MMA(1, 1, At, B1); PG8_BAR;
;         }
	s_waitcnt lgkmcnt(3)
	v_mfma_f32_16x16x32_bf16 v[116:119], v[194:197], v[144:147], v[116:119]
	s_setprio 1
	s_waitcnt lgkmcnt(2)
	v_mfma_f32_16x16x32_bf16 v[112:115], v[202:205], v[144:147], v[112:115]
	s_mov_b32 m0, s29
	v_lshl_add_u64 v[210:211], s[16:17], 0, v[156:157]
	v_mfma_f32_16x16x32_bf16 v[100:103], v[194:197], v[166:169], v[100:103]
	v_mfma_f32_16x16x32_bf16 v[96:99], v[202:205], v[166:169], v[96:99]
	v_mfma_f32_16x16x32_bf16 v[84:87], v[194:197], v[178:181], v[84:87]
	v_mfma_f32_16x16x32_bf16 v[80:83], v[202:205], v[178:181], v[80:83]
	v_mfma_f32_16x16x32_bf16 v[68:71], v[194:197], v[186:189], v[68:71]
	v_mfma_f32_16x16x32_bf16 v[64:67], v[202:205], v[186:189], v[64:67]
	s_waitcnt lgkmcnt(1)
	v_mfma_f32_16x16x32_bf16 v[116:119], v[198:201], v[148:151], v[116:119]
	s_waitcnt lgkmcnt(0)
	v_mfma_f32_16x16x32_bf16 v[112:115], v[206:209], v[148:151], v[112:115]
	v_mfma_f32_16x16x32_bf16 v[100:103], v[198:201], v[174:177], v[100:103]
	v_mfma_f32_16x16x32_bf16 v[96:99], v[206:209], v[174:177], v[96:99]
	v_mfma_f32_16x16x32_bf16 v[84:87], v[198:201], v[182:185], v[84:87]
	v_mfma_f32_16x16x32_bf16 v[80:83], v[206:209], v[182:185], v[80:83]
	v_mfma_f32_16x16x32_bf16 v[68:71], v[198:201], v[190:193], v[68:71]
	s_setprio 0
	v_mfma_f32_16x16x32_bf16 v[64:67], v[206:209], v[190:193], v[64:67]
	s_barrier
	ds_read_b128 v[144:147], v172 offset:49152
	ds_read_b128 v[166:169], v172 offset:51200
	ds_read_b128 v[178:181], v172 offset:53248
	ds_read_b128 v[186:189], v172 offset:55296
	ds_read_b128 v[148:151], v172 offset:50176
	ds_read_b128 v[174:177], v172 offset:52224
	ds_read_b128 v[182:185], v172 offset:54272
	ds_read_b128 v[190:193], v172 offset:56320
	global_load_lds_dwordx4 v[210:211], off
	s_mov_b32 m0, s30
	v_lshl_add_u64 v[210:211], s[16:17], 0, v[158:159]
	global_load_lds_dwordx4 v[210:211], off
	s_barrier
	s_waitcnt lgkmcnt(7)
	v_mfma_f32_16x16x32_bf16 v[60:63], v[128:131], v[144:147], v[60:63]
	s_setprio 1
	v_mfma_f32_16x16x32_bf16 v[56:59], v[136:139], v[144:147], v[56:59]
	s_waitcnt lgkmcnt(6)
	v_mfma_f32_16x16x32_bf16 v[44:47], v[128:131], v[166:169], v[44:47]
	v_mfma_f32_16x16x32_bf16 v[40:43], v[136:139], v[166:169], v[40:43]
	s_waitcnt lgkmcnt(5)
	v_mfma_f32_16x16x32_bf16 v[28:31], v[128:131], v[178:181], v[28:31]
	v_mfma_f32_16x16x32_bf16 v[24:27], v[136:139], v[178:181], v[24:27]
	s_waitcnt lgkmcnt(4)
	v_mfma_f32_16x16x32_bf16 v[12:15], v[128:131], v[186:189], v[12:15]
	v_mfma_f32_16x16x32_bf16 v[8:11], v[136:139], v[186:189], v[8:11]
	s_waitcnt lgkmcnt(3)
	v_mfma_f32_16x16x32_bf16 v[60:63], v[132:135], v[148:151], v[60:63]
	v_mfma_f32_16x16x32_bf16 v[56:59], v[140:143], v[148:151], v[56:59]
	s_waitcnt lgkmcnt(2)
	v_mfma_f32_16x16x32_bf16 v[44:47], v[132:135], v[174:177], v[44:47]
	v_mfma_f32_16x16x32_bf16 v[40:43], v[140:143], v[174:177], v[40:43]
	s_waitcnt lgkmcnt(1)
	v_mfma_f32_16x16x32_bf16 v[28:31], v[132:135], v[182:185], v[28:31]
	v_mfma_f32_16x16x32_bf16 v[24:27], v[140:143], v[182:185], v[24:27]
	s_waitcnt lgkmcnt(0)
	v_mfma_f32_16x16x32_bf16 v[12:15], v[132:135], v[190:193], v[12:15]
	s_setprio 0
	v_mfma_f32_16x16x32_bf16 v[8:11], v[140:143], v[190:193], v[8:11]
	s_barrier
	s_add_u32 s14, s14, 0x84000
	s_addc_u32 s15, s15, 0
	s_add_i32 s16, s40, s23
	s_mov_b32 m0, s16
	v_lshl_add_u64 v[128:129], s[14:15], 0, v[156:157]
	global_load_lds_dwordx4 v[128:129], off
	s_add_i32 m0, s16, 0x2000
	v_lshl_add_u64 v[128:129], s[14:15], 0, v[158:159]
	global_load_lds_dwordx4 v[128:129], off
	s_waitcnt vmcnt(6)
	s_barrier
	v_mfma_f32_16x16x32_bf16 v[52:55], v[194:197], v[144:147], v[52:55]
	s_setprio 1
	v_mfma_f32_16x16x32_bf16 v[48:51], v[202:205], v[144:147], v[48:51]
	s_add_i32 s38, s38, 2
	s_add_u32 s12, s12, 0x8000
	s_addc_u32 s13, s13, 0
	s_add_u32 s36, s36, 0x8000
	s_addc_u32 s37, s37, 0
	v_mfma_f32_16x16x32_bf16 v[36:39], v[194:197], v[166:169], v[36:39]
	v_mfma_f32_16x16x32_bf16 v[32:35], v[202:205], v[166:169], v[32:35]
	v_mfma_f32_16x16x32_bf16 v[20:23], v[194:197], v[178:181], v[20:23]
	v_mfma_f32_16x16x32_bf16 v[16:19], v[202:205], v[178:181], v[16:19]
	v_mfma_f32_16x16x32_bf16 v[4:7], v[194:197], v[186:189], v[4:7]
	v_mfma_f32_16x16x32_bf16 v[0:3], v[202:205], v[186:189], v[0:3]
	v_mfma_f32_16x16x32_bf16 v[52:55], v[198:201], v[148:151], v[52:55]
	v_mfma_f32_16x16x32_bf16 v[48:51], v[206:209], v[148:151], v[48:51]
	v_mfma_f32_16x16x32_bf16 v[36:39], v[198:201], v[174:177], v[36:39]
	v_mfma_f32_16x16x32_bf16 v[32:35], v[206:209], v[174:177], v[32:35]
	v_mfma_f32_16x16x32_bf16 v[20:23], v[198:201], v[182:185], v[20:23]
	v_mfma_f32_16x16x32_bf16 v[16:19], v[206:209], v[182:185], v[16:19]
	v_mfma_f32_16x16x32_bf16 v[4:7], v[198:201], v[190:193], v[4:7]
	s_cmp_gt_u32 s38, 29
	s_setprio 0
	v_mfma_f32_16x16x32_bf16 v[0:3], v[206:209], v[190:193], v[0:3]
	s_barrier
	s_cbranch_scc0 .LBB0_247
